# P2: B rows re-permuted so a wave's two column halves are adjacent; hand-written epilogue pairs them (DPP row_ror:8) into whole-128-byte-line stores
# baseline (speedup 1.0000x reference)
; #define PG8_WAIT_V(n) asm volatile("s_waitcnt vmcnt(" #n ")" ::: "memory")
; template <class Epi, class Sched, bool ALIGN_EPI = false, bool SP2 = false>
; __device__ __forceinline__ void gemm_phase(PG8_LAS unsigned char* lds, const Gemm g, const Sched& S, const Epi& E) {
;     int tid_l_ = threadIdx.x; asm volatile("" : "+v"(tid_l_));
;     const int tid = tid_l_, wid = __builtin_amdgcn_readfirstlane(tid >> 6), lane = tid & 63, wr = wid >> 2, wc = wid & 3, fr = lane & 15, fq = lane >> 4;
;     const int K = g.K, nt = K / BK;
;     unsigned voffA[2], voffB[2];
; #pragma unroll
;     for (int i = 0; i < 2; ++i) { int R, C; stage_rc(tid * 16 + i * 8192, R, C); const int Rb = Epi::PERM ? ((R & ~31) + perm32(R & 31)) : R;
;         voffA[i] = (unsigned)(R * K + C) * 2u; voffB[i] = (unsigned)(Rb * K + C) * 2u; }
;     const size_t kstep = (size_t)(BK * 2);
;     const size_t hstep = (size_t)HALF * K * 2;
;     const size_t tstep = 2 * hstep;
;     const unsigned ldsw = (unsigned)wid * 1024u;
;     const int aoff = lds_byte(wr * 64 + fr, fq * 8), boff = lds_byte(wc * 32 + fr, fq * 8);
;     ...
;     Unit cur, nxt; int ui = 0;
;     if (!S.next(0, cur)) return;
;     f32x4 acc[2][2][4][2];
; #pragma unroll
;     for (int a = 0; a < 2; ++a)
; #pragma unroll
;         for (int b = 0; b < 2; ++b)
; #pragma unroll
;             for (int m = 0; m < 4; ++m)
; #pragma unroll
;                 for (int n = 0; n < 2; ++n) acc[a][b][m][n] = (f32x4){0.f, 0.f, 0.f, 0.f};
;     bf16x8 At[4][2], B0[2][2], B1[2][2];
;     const char* cA = (const char*)g.A + (size_t)cur.pm * tstep; const char* cB = (const char*)g.Bt + (size_t)cur.pn * tstep;
;     S.a_ready(cur);
;     if constexpr (SP2) {
;         PG8_STAGE(PG8_SB(0, 0), cB, voffB); PG8_STAGE(PG8_SB(0, 1), cB + hstep, voffB); PG8_STAGE(PG8_SA(0, 0), cA, voffA); PG8_STAGE(PG8_SA(0, 1), cA + hstep, voffA);
;         if (wr == 1) PG8_BAR;
;         PG8_WAIT_V(2); PG8_BAR;
;         PG8_STAGE(PG8_SB(1, 0), cB + kstep, voffB); PG8_STAGE(PG8_SA(1, 0), cA + kstep, voffA); PG8_STAGE(PG8_SB(1, 1), cB + hstep + kstep, voffB);
;         PG8_WAIT_V(6); PG8_BAR;
;     } else {
;         PG8_STAGE(PG8_SB(0, 0), cB, voffB); PG8_STAGE(PG8_SA(0, 0), cA, voffA); PG8_STAGE(PG8_SB(0, 1), cB + hstep, voffB); PG8_STAGE(PG8_SA(0, 1), cA + hstep, voffA);
;         if (wr == 1) PG8_BAR;
;         PG8_WAIT_V(4); PG8_BAR;
.LBB0_257:
	s_add_u32 s18, s78, 0x3200000
	s_addc_u32 s19, s79, 0
	s_andn2_b64 vcc, exec, s[0:1]
	s_cbranch_vccnz .LBB0_313
	v_ashrrev_i32_e32 v2, 31, v10
	v_lshrrev_b32_e32 v2, 26, v2
	v_add_u32_e32 v2, v10, v2
	v_ashrrev_i32_e32 v11, 6, v2
	v_bfe_i32 v2, v10, 27, 1
	v_lshlrev_b32_e32 v1, 4, v10
	v_lshrrev_b32_e32 v2, 22, v2
	v_add_u32_e32 v2, v1, v2
	v_and_b32_e32 v2, 0xfffffc00, v2
	v_sub_u32_e32 v2, v1, v2
	v_lshrrev_b32_e32 v3, 4, v2
	v_bitop3_b32 v2, v3, v2, 32 bitop3:0x6c
	v_ashrrev_i32_e32 v4, 31, v2
	v_lshrrev_b32_e32 v4, 26, v4
	v_add_u32_e32 v4, v2, v4
	v_lshlrev_b32_e32 v3, 3, v11
	v_ashrrev_i32_e32 v12, 6, v4
	v_and_b32_e32 v4, 0xc0, v4
	v_and_b32_e32 v3, -16, v3
	v_sub_u32_e32 v2, v2, v4
	v_mov_b32_e32 v4, 1
	v_add_u32_e32 v3, v12, v3
	v_ashrrev_i16_sdwa v2, v4, sext(v2) dst_sel:DWORD dst_unused:UNUSED_PAD src0_sel:DWORD src1_sel:BYTE_0
	v_lshlrev_b32_e32 v5, 5, v11
	v_bfe_i32 v13, v2, 0, 16
	v_lshlrev_b32_e32 v2, 1, v3
	v_lshrrev_b32_e32 v6, 2, v3
	v_and_b32_e32 v7, 3, v12
	s_mov_b32 s1, 0x1fffe0
	v_and_b32_e32 v5, 32, v5
	v_and_b32_e32 v2, 24, v2
	v_and_b32_e32 v6, 4, v6
	v_and_or_b32 v7, v3, s1, v7
	v_or3_b32 v2, v7, v6, v2
	v_add_lshl_u32 v5, v5, v13, 1
	v_add_u32_e32 v1, 0x2000, v1
	v_lshl_add_u32 v132, v2, 11, v5
	v_and_b32_e32 v226, 0x30000, v132
	v_add_u32_e32 v132, v132, v226
	v_ashrrev_i32_e32 v2, 31, v1
	v_lshrrev_b32_e32 v2, 22, v2
	v_add_u32_e32 v2, v1, v2
	v_ashrrev_i32_e32 v14, 10, v2
	v_mul_i32_i24_e32 v2, 0x400, v14
	v_sub_u32_e32 v1, v1, v2
	v_lshrrev_b32_e32 v2, 4, v1
	v_bitop3_b32 v1, v2, v1, 32 bitop3:0x6c
	v_lshl_add_u32 v130, v3, 11, v5
	v_ashrrev_i32_e32 v3, 31, v1
	v_lshrrev_b32_e32 v3, 26, v3
	v_add_u32_e32 v3, v1, v3
	v_lshlrev_b32_e32 v2, 3, v14
	v_ashrrev_i32_e32 v15, 6, v3
	v_and_b32_e32 v3, 0xc0, v3
	v_and_b32_e32 v2, -16, v2
	v_sub_u32_e32 v1, v1, v3
	v_add_u32_e32 v2, v15, v2
	v_ashrrev_i16_sdwa v1, v4, sext(v1) dst_sel:DWORD dst_unused:UNUSED_PAD src0_sel:DWORD src1_sel:BYTE_0
	v_and_b32_e32 v4, 3, v15
	v_and_or_b32 v4, v2, s1, v4
	s_ashr_i32 s1, s20, 6
	s_ashr_i32 s7, s6, 31
	s_ashr_i32 s87, s86, 31
	s_ashr_i32 s0, s20, 8
	s_lshl_b32 s12, s1, 10
	s_lshl_b64 s[4:5], s[6:7], 19
	s_lshl_b64 s[26:27], s[86:87], 19
	s_add_u32 s90, s8, s26
	v_lshlrev_b32_e32 v5, 5, v14
	v_bfe_i32 v16, v1, 0, 16
	v_lshlrev_b32_e32 v1, 1, v2
	v_lshrrev_b32_e32 v3, 2, v2
	s_addc_u32 s91, s9, s27
	s_add_i32 s13, s12, 0
	v_and_b32_e32 v5, 32, v5
	v_and_b32_e32 v1, 24, v1
	v_and_b32_e32 v3, 4, v3
	s_add_i32 m0, s13, 0x10000
	v_or3_b32 v1, v4, v3, v1
	v_add_lshl_u32 v3, v5, v16, 1
	global_load_lds_dwordx4 v132, s[90:91]
	s_add_i32 m0, s13, 0x12000
	v_lshl_add_u32 v136, v1, 11, v3
	v_and_b32_e32 v226, 0x30000, v136
	v_add_u32_e32 v136, v136, v226
	s_add_u32 s26, s90, 0x10000
	global_load_lds_dwordx4 v136, s[90:91]
	s_addc_u32 s27, s91, 0
	s_add_i32 m0, s13, 0x14000
	v_lshl_add_u32 v134, v2, 11, v3
	global_load_lds_dwordx4 v132, s[26:27]
	s_add_i32 m0, s13, 0x16000
	s_add_u32 s88, s76, s4
	s_addc_u32 s89, s77, s5
	s_add_i32 s34, s13, 0x2000
	global_load_lds_dwordx4 v136, s[26:27]
	s_mov_b32 m0, s13
	s_add_u32 s4, s88, 0x40000
	global_load_lds_dwordx4 v130, s[88:89]
	s_mov_b32 m0, s34
	s_addc_u32 s5, s89, 0
	s_add_i32 s35, s13, 0x4000
	global_load_lds_dwordx4 v134, s[88:89]
	s_mov_b32 m0, s35
	s_add_i32 s70, s13, 0x6000
	global_load_lds_dwordx4 v130, s[4:5]
	s_mov_b32 m0, s70
	v_mov_b32_e32 v133, 0
	global_load_lds_dwordx4 v134, s[4:5]
	v_mov_b32_e32 v137, v133
	v_mov_b32_e32 v131, v133
	v_mov_b32_e32 v135, v133
	s_cmp_eq_u32 s0, 1
	s_mov_b32 s21, 0
	v_lshl_add_u64 v[8:9], s[90:91], 0, v[132:133]
	v_lshl_add_u64 v[6:7], s[90:91], 0, v[136:137]
	v_lshl_add_u64 v[2:3], s[88:89], 0, v[130:131]
	s_cselect_b64 s[26:27], -1, 0
	s_cmp_lg_u32 s0, 1
	v_lshl_add_u64 v[4:5], s[88:89], 0, v[134:135]
	s_cbranch_scc1 .LBB0_260
	s_barrier
.LBB0_260:
	s_lshl_b32 s1, s1, 5
	s_mov_b64 s[28:29], 0x80
	s_and_b32 s1, s1, 0x60
	s_add_i32 m0, s13, 0x18000
	v_lshl_add_u64 v[8:9], v[8:9], 0, s[28:29]
	s_lshl_b32 s3, s0, 13
	s_lshl_b32 s7, s1, 7
	s_waitcnt vmcnt(2)
	s_barrier
	global_load_lds_dwordx4 v[8:9], off
	v_lshl_add_u64 v[6:7], v[6:7], 0, s[28:29]
	s_add_i32 m0, s13, 0x1a000
	s_add_i32 s71, s13, 0x8000
	s_add_i32 s72, s13, 0xa000
	global_load_lds_dwordx4 v[6:7], off
	v_lshl_add_u64 v[2:3], v[2:3], 0, s[28:29]
	s_mov_b32 m0, s71
	s_add_u32 s4, s90, 0x10080
	global_load_lds_dwordx4 v[2:3], off
	v_lshl_add_u64 v[2:3], v[4:5], 0, s[28:29]
	s_mov_b32 m0, s72
	s_addc_u32 s5, s91, 0
	global_load_lds_dwordx4 v[2:3], off
	s_add_i32 m0, s13, 0x1c000
	v_lshl_add_u64 v[2:3], s[4:5], 0, v[132:133]
	global_load_lds_dwordx4 v[2:3], off
	v_lshl_add_u64 v[2:3], s[4:5], 0, v[136:137]
	s_add_i32 m0, s13, 0x1e000
	s_cmpk_lt_u32 s20, 0x100
	global_load_lds_dwordx4 v[2:3], off
	v_lshrrev_b32_e32 v3, 1, v10
	v_and_b32_e32 v3, 24, v3
	v_and_b32_e32 v2, 15, v10
	v_lshlrev_b32_e32 v4, 1, v3
	v_lshl_or_b32 v1, s0, 6, v2
	v_lshl_or_b32 v2, v2, 6, v4
	v_lshlrev_b32_e32 v4, 2, v10
	v_and_b32_e32 v4, 32, v4
	v_bitop3_b32 v5, v2, s3, v4 bitop3:0xde
	v_bitop3_b32 v150, v2, s7, v4 bitop3:0xde
	v_lshlrev_b32_e32 v2, 14, v11
	v_and_b32_e32 v2, 0xffff8000, v2
	v_or_b32_e32 v151, s1, v3
	v_lshl_add_u32 v2, v12, 11, v2
	v_and_b32_e32 v3, 1, v11
	v_lshl_or_b32 v2, v3, 6, v2
	v_lshl_add_u32 v138, v13, 1, v2
	v_lshlrev_b32_e32 v2, 14, v14
	v_and_b32_e32 v2, 0xffff8000, v2
	s_waitcnt vmcnt(6)
	v_lshl_add_u32 v2, v15, 11, v2
	v_and_b32_e32 v3, 1, v14
	s_cselect_b64 s[56:57], -1, 0
	v_lshl_or_b32 v2, v3, 6, v2
	s_add_i32 s75, 0, 0x14000
	s_movk_i32 s73, 0x100
	s_ashr_i32 s74, s2, 31
	v_mov_b32_e32 v139, v133
	v_lshl_add_u32 v140, v16, 1, v2
	v_mov_b32_e32 v141, v133
	v_mov_b64_e32 v[142:143], 0x2ec
	v_mov_b64_e32 v[144:145], 0x2eb
	v_add_u32_e32 v152, s33, v150
	v_add_u32_e32 v153, s75, v150
	v_add_u32_e32 v154, 0, v5
	s_movk_i32 s94, 0xb40
	s_movk_i32 s95, 0x1680
	v_mov_b32_e32 v155, 0x3e000000
	s_mov_b32 s20, s21
	s_barrier
	s_branch .LBB0_263

; #define PG8_STAGE(bufoff, gbase, voff) do { _Pragma("unroll") for (int _i = 0; _i < 2; ++_i) \
;         __builtin_amdgcn_global_load_lds((const unsigned*)((const char*)(gbase) + (voff)[_i]), (PG8_LAS unsigned*)(lds + (bufoff) + ldsw + _i * 8192), 16, 0, 0); } while (0)
; #define PG8_LDA(dst, b, h) do { _Pragma("unroll") for (int m = 0; m < 4; ++m) _Pragma("unroll") for (int k = 0; k < 2; ++k) dst[m][k] = *(const PG8_LAS bf16x8*)(lds + PG8_SA(b, h) + aoff + m * 2048 + k * 1024); } while (0)
; #define PG8_LDB(dst, b, h) do { _Pragma("unroll") for (int n = 0; n < 2; ++n) _Pragma("unroll") for (int k = 0; k < 2; ++k) dst[n][k] = *(const PG8_LAS bf16x8*)(lds + PG8_SB(b, h) + boff + n * 2048 + k * 1024); } while (0)
; #define PG8_MMA(ai, bj, At, Bt) do { __builtin_amdgcn_s_setprio(1); _Pragma("unroll") for (int m = 0; m < 4; ++m) _Pragma("unroll") for (int n = 0; n < 2; ++n) _Pragma("unroll") for (int k = 0; k < 2; ++k) \
;         acc[ai][bj][m][n] = __builtin_amdgcn_mfma_f32_16x16x32_bf16(Bt[n][k], At[m][k], acc[ai][bj][m][n], 0, 0, 0); __builtin_amdgcn_s_setprio(0); } while (0)
; #define PG8_WAIT_V(n) asm volatile("s_waitcnt vmcnt(" #n ")" ::: "memory")
; #define PG8_WAIT_L(n) asm volatile("s_waitcnt lgkmcnt(" #n ")" ::: "memory")
; #define PG8_BAR __builtin_amdgcn_s_barrier()
; #define PG8_SCHED __builtin_amdgcn_sched_barrier(0)
; template <class Epi, class Sched, bool ALIGN_EPI = false, bool SP2 = false>
; __device__ __forceinline__ void gemm_phase(PG8_LAS unsigned char* lds, const Gemm g, const Sched& S, const Epi& E) {
;     ...
;             PG8_LDB(B0, 0, 0); PG8_LDB(B1, 0, 1); PG8_SCHED; PG8_LDA(At, 0, 0); PG8_STAGE(PG8_SA(1, 1), a1 + hstep, voffA);
;             PG8_WAIT_V(8); PG8_WAIT_L(0); PG8_BAR; PG8_MMA(0, 0, At, B0); PG8_MMA(0, 1, At, B1); PG8_BAR; PG8_SCHED;
;             PG8_LDA(At, 0, 1); PG8_STAGE(PG8_SB(0, 0), b2, voffB); PG8_STAGE(PG8_SB(0, 1), b2 + hstep, voffB); PG8_STAGE(PG8_SA(0, 0), a2, voffA);
;             PG8_WAIT_V(8); PG8_WAIT_L(0); PG8_BAR; PG8_MMA(1, 0, At, B0); PG8_MMA(1, 1, At, B1); PG8_BAR; PG8_SCHED;
.LBB0_270:
	ds_read_b128 v[146:149], v152
	ds_read_b128 v[156:159], v152 offset:1024
	ds_read_b128 v[160:163], v152 offset:2048
	ds_read_b128 v[164:167], v152 offset:3072
	ds_read_b128 v[168:171], v153
	ds_read_b128 v[172:175], v153 offset:1024
	ds_read_b128 v[176:179], v153 offset:2048
	ds_read_b128 v[180:183], v153 offset:3072
	s_add_u32 s3, s88, 0xfffc0080
	s_addc_u32 s90, s89, -1
	s_cmp_eq_u32 s96, 12
	s_cselect_b32 s93, s0, s90
	s_cselect_b32 s92, s1, s3
	s_cselect_b32 s91, s7, s87
	s_cselect_b32 s90, s69, s81
	v_lshl_add_u64 v[216:217], s[88:89], 0, v[138:139]
	s_add_i32 m0, s13, 0xc000
	ds_read_b128 v[184:187], v154
	ds_read_b128 v[188:191], v154 offset:1024
	ds_read_b128 v[192:195], v154 offset:2048
	ds_read_b128 v[196:199], v154 offset:3072
	ds_read_b128 v[200:203], v154 offset:4096
	ds_read_b128 v[204:207], v154 offset:5120
	ds_read_b128 v[208:211], v154 offset:6144
	ds_read_b128 v[212:215], v154 offset:7168
	global_load_lds_dwordx4 v[216:217], off
	v_lshl_add_u64 v[216:217], s[88:89], 0, v[140:141]
	s_add_i32 m0, s13, 0xe000
	s_nop 0
	global_load_lds_dwordx4 v[216:217], off
	s_waitcnt vmcnt(8)
	s_waitcnt lgkmcnt(0)
	s_barrier
	s_setprio 1
	s_waitcnt lgkmcnt(0)
	v_mfma_f32_16x16x32_bf16 v[126:129], v[146:149], v[184:187], v[126:129]
	v_mfma_f32_16x16x32_bf16 v[122:125], v[160:163], v[184:187], v[122:125]
	v_mfma_f32_16x16x32_bf16 v[118:121], v[146:149], v[192:195], v[118:121]
	v_mfma_f32_16x16x32_bf16 v[114:117], v[160:163], v[192:195], v[114:117]
	v_mfma_f32_16x16x32_bf16 v[110:113], v[146:149], v[200:203], v[110:113]
	v_mfma_f32_16x16x32_bf16 v[106:109], v[160:163], v[200:203], v[106:109]
	v_mfma_f32_16x16x32_bf16 v[102:105], v[146:149], v[208:211], v[102:105]
	v_mfma_f32_16x16x32_bf16 v[98:101], v[160:163], v[208:211], v[98:101]
	v_mfma_f32_16x16x32_bf16 v[126:129], v[156:159], v[188:191], v[126:129]
	v_mfma_f32_16x16x32_bf16 v[122:125], v[164:167], v[188:191], v[122:125]
	v_mfma_f32_16x16x32_bf16 v[118:121], v[156:159], v[196:199], v[118:121]
	v_mfma_f32_16x16x32_bf16 v[114:117], v[164:167], v[196:199], v[114:117]
	v_mfma_f32_16x16x32_bf16 v[110:113], v[156:159], v[204:207], v[110:113]
	v_mfma_f32_16x16x32_bf16 v[106:109], v[164:167], v[204:207], v[106:109]
	v_mfma_f32_16x16x32_bf16 v[102:105], v[156:159], v[212:215], v[102:105]
	v_mfma_f32_16x16x32_bf16 v[98:101], v[164:167], v[212:215], v[98:101]
	s_setprio 0
	s_setprio 1
	v_mfma_f32_16x16x32_bf16 v[62:65], v[168:171], v[184:187], v[62:65]
	v_mfma_f32_16x16x32_bf16 v[58:61], v[176:179], v[184:187], v[58:61]
	v_mfma_f32_16x16x32_bf16 v[54:57], v[168:171], v[192:195], v[54:57]
	v_mfma_f32_16x16x32_bf16 v[50:53], v[176:179], v[192:195], v[50:53]
	v_mfma_f32_16x16x32_bf16 v[46:49], v[168:171], v[200:203], v[46:49]
	v_mfma_f32_16x16x32_bf16 v[42:45], v[176:179], v[200:203], v[42:45]
	v_mfma_f32_16x16x32_bf16 v[38:41], v[168:171], v[208:211], v[38:41]
	v_mfma_f32_16x16x32_bf16 v[34:37], v[176:179], v[208:211], v[34:37]
	v_mfma_f32_16x16x32_bf16 v[62:65], v[172:175], v[188:191], v[62:65]
	v_mfma_f32_16x16x32_bf16 v[58:61], v[180:183], v[188:191], v[58:61]
	v_mfma_f32_16x16x32_bf16 v[54:57], v[172:175], v[196:199], v[54:57]
	v_mfma_f32_16x16x32_bf16 v[50:53], v[180:183], v[196:199], v[50:53]
	v_mfma_f32_16x16x32_bf16 v[46:49], v[172:175], v[204:207], v[46:49]
	v_mfma_f32_16x16x32_bf16 v[42:45], v[180:183], v[204:207], v[42:45]
	v_mfma_f32_16x16x32_bf16 v[38:41], v[172:175], v[212:215], v[38:41]
	v_mfma_f32_16x16x32_bf16 v[34:37], v[180:183], v[212:215], v[34:37]
	s_setprio 0
	s_barrier
	s_add_i32 s3, s33, s12
	v_lshl_add_u64 v[216:217], s[90:91], 0, v[132:133]
	s_mov_b32 m0, s3
	ds_read_b128 v[184:187], v154 offset:16384
	ds_read_b128 v[188:191], v154 offset:17408
	ds_read_b128 v[192:195], v154 offset:18432
	ds_read_b128 v[196:199], v154 offset:19456
	ds_read_b128 v[200:203], v154 offset:20480
	ds_read_b128 v[204:207], v154 offset:21504
	ds_read_b128 v[208:211], v154 offset:22528
	ds_read_b128 v[212:215], v154 offset:23552
	global_load_lds_dwordx4 v[216:217], off
	s_add_i32 m0, s3, 0x2000
	s_add_u32 vcc_lo, s90, 0x10000
	v_lshl_add_u64 v[218:219], s[90:91], 0, v[136:137]
	s_addc_u32 vcc_hi, s91, 0
	s_add_i32 s3, s75, s12
	global_load_lds_dwordx4 v[218:219], off
	v_lshl_add_u64 v[220:221], vcc, 0, v[132:133]
	s_mov_b32 m0, s3
	v_lshl_add_u64 v[222:223], s[92:93], 0, v[134:135]
	global_load_lds_dwordx4 v[220:221], off
	v_lshl_add_u64 v[220:221], vcc, 0, v[136:137]
	s_add_i32 m0, s3, 0x2000
	s_nop 0
	global_load_lds_dwordx4 v[220:221], off
	v_lshl_add_u64 v[220:221], s[92:93], 0, v[130:131]
	s_mov_b32 m0, s13
	s_nop 0
	global_load_lds_dwordx4 v[220:221], off
	s_mov_b32 m0, s34
	s_nop 0
	global_load_lds_dwordx4 v[222:223], off
	s_waitcnt vmcnt(8)
	s_waitcnt lgkmcnt(0)
	s_barrier
; #define PG8_STAGE(bufoff, gbase, voff) do { _Pragma("unroll") for (int _i = 0; _i < 2; ++_i) \
;         __builtin_amdgcn_global_load_lds((const unsigned*)((const char*)(gbase) + (voff)[_i]), (PG8_LAS unsigned*)(lds + (bufoff) + ldsw + _i * 8192), 16, 0, 0); } while (0)
; #define PG8_LDA(dst, b, h) do { _Pragma("unroll") for (int m = 0; m < 4; ++m) _Pragma("unroll") for (int k = 0; k < 2; ++k) dst[m][k] = *(const PG8_LAS bf16x8*)(lds + PG8_SA(b, h) + aoff + m * 2048 + k * 1024); } while (0)
; #define PG8_LDB(dst, b, h) do { _Pragma("unroll") for (int n = 0; n < 2; ++n) _Pragma("unroll") for (int k = 0; k < 2; ++k) dst[n][k] = *(const PG8_LAS bf16x8*)(lds + PG8_SB(b, h) + boff + n * 2048 + k * 1024); } while (0)
; #define PG8_MMA(ai, bj, At, Bt) do { __builtin_amdgcn_s_setprio(1); _Pragma("unroll") for (int m = 0; m < 4; ++m) _Pragma("unroll") for (int n = 0; n < 2; ++n) _Pragma("unroll") for (int k = 0; k < 2; ++k) \
;         acc[ai][bj][m][n] = __builtin_amdgcn_mfma_f32_16x16x32_bf16(Bt[n][k], At[m][k], acc[ai][bj][m][n], 0, 0, 0); __builtin_amdgcn_s_setprio(0); } while (0)
; #define PG8_WAIT_V(n) asm volatile("s_waitcnt vmcnt(" #n ")" ::: "memory")
; #define PG8_WAIT_L(n) asm volatile("s_waitcnt lgkmcnt(" #n ")" ::: "memory")
; #define PG8_BAR __builtin_amdgcn_s_barrier()
; #define PG8_SCHED __builtin_amdgcn_sched_barrier(0)
; template <class Epi, class Sched, bool ALIGN_EPI = false, bool SP2 = false>
; __device__ __forceinline__ void gemm_phase(PG8_LAS unsigned char* lds, const Gemm g, const Sched& S, const Epi& E) {
;     ...
;             PG8_WAIT_V(8); PG8_WAIT_L(0); PG8_BAR; PG8_MMA(1, 0, At, B0); PG8_MMA(1, 1, At, B1); PG8_BAR; PG8_SCHED;
;             PG8_LDB(B0, 1, 0); PG8_LDB(B1, 1, 1); PG8_SCHED; PG8_LDA(At, 1, 0); PG8_STAGE(PG8_SA(0, 1), a2 + hstep, voffA);
;             PG8_WAIT_V(8); PG8_WAIT_L(0); PG8_BAR; PG8_MMA(0, 0, At, B0); PG8_MMA(0, 1, At, B1); PG8_BAR; PG8_SCHED;
	s_setprio 1
	s_waitcnt lgkmcnt(0)
	v_mfma_f32_16x16x32_bf16 v[94:97], v[146:149], v[184:187], v[94:97]
	v_mfma_f32_16x16x32_bf16 v[90:93], v[160:163], v[184:187], v[90:93]
	v_mfma_f32_16x16x32_bf16 v[86:89], v[146:149], v[192:195], v[86:89]
	v_mfma_f32_16x16x32_bf16 v[82:85], v[160:163], v[192:195], v[82:85]
	v_mfma_f32_16x16x32_bf16 v[78:81], v[146:149], v[200:203], v[78:81]
	v_mfma_f32_16x16x32_bf16 v[74:77], v[160:163], v[200:203], v[74:77]
	v_mfma_f32_16x16x32_bf16 v[70:73], v[146:149], v[208:211], v[70:73]
	v_mfma_f32_16x16x32_bf16 v[66:69], v[160:163], v[208:211], v[66:69]
	v_mfma_f32_16x16x32_bf16 v[94:97], v[156:159], v[188:191], v[94:97]
	v_mfma_f32_16x16x32_bf16 v[90:93], v[164:167], v[188:191], v[90:93]
	v_mfma_f32_16x16x32_bf16 v[86:89], v[156:159], v[196:199], v[86:89]
	v_mfma_f32_16x16x32_bf16 v[82:85], v[164:167], v[196:199], v[82:85]
	v_mfma_f32_16x16x32_bf16 v[78:81], v[156:159], v[204:207], v[78:81]
	v_mfma_f32_16x16x32_bf16 v[74:77], v[164:167], v[204:207], v[74:77]
	v_mfma_f32_16x16x32_bf16 v[70:73], v[156:159], v[212:215], v[70:73]
	v_mfma_f32_16x16x32_bf16 v[66:69], v[164:167], v[212:215], v[66:69]
	s_setprio 0
	s_setprio 1
	v_mfma_f32_16x16x32_bf16 v[30:33], v[168:171], v[184:187], v[30:33]
	v_mfma_f32_16x16x32_bf16 v[26:29], v[176:179], v[184:187], v[26:29]
	v_mfma_f32_16x16x32_bf16 v[22:25], v[168:171], v[192:195], v[22:25]
	v_mfma_f32_16x16x32_bf16 v[18:21], v[176:179], v[192:195], v[18:21]
	v_mfma_f32_16x16x32_bf16 v[14:17], v[168:171], v[200:203], v[14:17]
	v_mfma_f32_16x16x32_bf16 v[10:13], v[176:179], v[200:203], v[10:13]
	v_mfma_f32_16x16x32_bf16 v[6:9], v[168:171], v[208:211], v[6:9]
	v_mfma_f32_16x16x32_bf16 v[2:5], v[176:179], v[208:211], v[2:5]
	v_mfma_f32_16x16x32_bf16 v[30:33], v[172:175], v[188:191], v[30:33]
	v_mfma_f32_16x16x32_bf16 v[26:29], v[180:183], v[188:191], v[26:29]
	v_mfma_f32_16x16x32_bf16 v[22:25], v[172:175], v[196:199], v[22:25]
	v_mfma_f32_16x16x32_bf16 v[18:21], v[180:183], v[196:199], v[18:21]
	v_mfma_f32_16x16x32_bf16 v[14:17], v[172:175], v[204:207], v[14:17]
	v_mfma_f32_16x16x32_bf16 v[10:13], v[180:183], v[204:207], v[10:13]
	v_mfma_f32_16x16x32_bf16 v[6:9], v[172:175], v[212:215], v[6:9]
	v_mfma_f32_16x16x32_bf16 v[2:5], v[180:183], v[212:215], v[2:5]
	s_setprio 0
	s_barrier
	s_add_i32 s3, 0, 0x18000
	s_add_i32 s97, 0, 0x1c000
	v_add_u32_e32 v164, s3, v150
	v_add_u32_e32 v180, s97, v150
	ds_read_b128 v[146:149], v164
	ds_read_b128 v[156:159], v164 offset:1024
	ds_read_b128 v[160:163], v164 offset:2048
	ds_read_b128 v[164:167], v164 offset:3072
	ds_read_b128 v[168:171], v180
	ds_read_b128 v[172:175], v180 offset:1024
	ds_read_b128 v[176:179], v180 offset:2048
	ds_read_b128 v[180:183], v180 offset:3072
	s_add_u32 s92, s92, 0x40000
	s_addc_u32 s93, s93, 0
	s_mov_b32 m0, s35
	v_lshl_add_u64 v[224:225], s[92:93], 0, v[130:131]
	ds_read_b128 v[184:187], v154 offset:32768
	ds_read_b128 v[188:191], v154 offset:33792
	ds_read_b128 v[192:195], v154 offset:34816
	ds_read_b128 v[196:199], v154 offset:35840
	ds_read_b128 v[200:203], v154 offset:36864
	ds_read_b128 v[204:207], v154 offset:37888
	ds_read_b128 v[208:211], v154 offset:38912
	ds_read_b128 v[212:215], v154 offset:39936
	global_load_lds_dwordx4 v[224:225], off
	v_lshl_add_u64 v[224:225], s[92:93], 0, v[134:135]
	s_mov_b32 m0, s70
	s_nop 0
	global_load_lds_dwordx4 v[224:225], off
	s_waitcnt vmcnt(8)
	s_waitcnt lgkmcnt(0)
	s_barrier
	s_setprio 1
	s_waitcnt lgkmcnt(0)
	v_mfma_f32_16x16x32_bf16 v[126:129], v[146:149], v[184:187], v[126:129]
	v_mfma_f32_16x16x32_bf16 v[122:125], v[160:163], v[184:187], v[122:125]
	v_mfma_f32_16x16x32_bf16 v[118:121], v[146:149], v[192:195], v[118:121]
	v_mfma_f32_16x16x32_bf16 v[114:117], v[160:163], v[192:195], v[114:117]
	v_mfma_f32_16x16x32_bf16 v[110:113], v[146:149], v[200:203], v[110:113]
	v_mfma_f32_16x16x32_bf16 v[106:109], v[160:163], v[200:203], v[106:109]
	v_mfma_f32_16x16x32_bf16 v[102:105], v[146:149], v[208:211], v[102:105]
	v_mfma_f32_16x16x32_bf16 v[98:101], v[160:163], v[208:211], v[98:101]
	v_mfma_f32_16x16x32_bf16 v[126:129], v[156:159], v[188:191], v[126:129]
	v_mfma_f32_16x16x32_bf16 v[122:125], v[164:167], v[188:191], v[122:125]
	v_mfma_f32_16x16x32_bf16 v[118:121], v[156:159], v[196:199], v[118:121]
	v_mfma_f32_16x16x32_bf16 v[114:117], v[164:167], v[196:199], v[114:117]
	v_mfma_f32_16x16x32_bf16 v[110:113], v[156:159], v[204:207], v[110:113]
	v_mfma_f32_16x16x32_bf16 v[106:109], v[164:167], v[204:207], v[106:109]
	v_mfma_f32_16x16x32_bf16 v[102:105], v[156:159], v[212:215], v[102:105]
	v_mfma_f32_16x16x32_bf16 v[98:101], v[164:167], v[212:215], v[98:101]
	s_setprio 0
	s_setprio 1
	v_mfma_f32_16x16x32_bf16 v[62:65], v[168:171], v[184:187], v[62:65]
	v_mfma_f32_16x16x32_bf16 v[58:61], v[176:179], v[184:187], v[58:61]
	v_mfma_f32_16x16x32_bf16 v[54:57], v[168:171], v[192:195], v[54:57]
	v_mfma_f32_16x16x32_bf16 v[50:53], v[176:179], v[192:195], v[50:53]
	v_mfma_f32_16x16x32_bf16 v[46:49], v[168:171], v[200:203], v[46:49]
	v_mfma_f32_16x16x32_bf16 v[42:45], v[176:179], v[200:203], v[42:45]
	v_mfma_f32_16x16x32_bf16 v[38:41], v[168:171], v[208:211], v[38:41]
	v_mfma_f32_16x16x32_bf16 v[34:37], v[176:179], v[208:211], v[34:37]
	v_mfma_f32_16x16x32_bf16 v[62:65], v[172:175], v[188:191], v[62:65]
	v_mfma_f32_16x16x32_bf16 v[58:61], v[180:183], v[188:191], v[58:61]
	v_mfma_f32_16x16x32_bf16 v[54:57], v[172:175], v[196:199], v[54:57]
	v_mfma_f32_16x16x32_bf16 v[50:53], v[180:183], v[196:199], v[50:53]
	v_mfma_f32_16x16x32_bf16 v[46:49], v[172:175], v[204:207], v[46:49]
	v_mfma_f32_16x16x32_bf16 v[42:45], v[180:183], v[204:207], v[42:45]
	v_mfma_f32_16x16x32_bf16 v[38:41], v[172:175], v[212:215], v[38:41]
	v_mfma_f32_16x16x32_bf16 v[34:37], v[180:183], v[212:215], v[34:37]
	s_setprio 0
	s_barrier
; #define PG8_STAGE(bufoff, gbase, voff) do { _Pragma("unroll") for (int _i = 0; _i < 2; ++_i) \
;         __builtin_amdgcn_global_load_lds((const unsigned*)((const char*)(gbase) + (voff)[_i]), (PG8_LAS unsigned*)(lds + (bufoff) + ldsw + _i * 8192), 16, 0, 0); } while (0)
; #define PG8_LDA(dst, b, h) do { _Pragma("unroll") for (int m = 0; m < 4; ++m) _Pragma("unroll") for (int k = 0; k < 2; ++k) dst[m][k] = *(const PG8_LAS bf16x8*)(lds + PG8_SA(b, h) + aoff + m * 2048 + k * 1024); } while (0)
; #define PG8_MMA(ai, bj, At, Bt) do { __builtin_amdgcn_s_setprio(1); _Pragma("unroll") for (int m = 0; m < 4; ++m) _Pragma("unroll") for (int n = 0; n < 2; ++n) _Pragma("unroll") for (int k = 0; k < 2; ++k) \
;         acc[ai][bj][m][n] = __builtin_amdgcn_mfma_f32_16x16x32_bf16(Bt[n][k], At[m][k], acc[ai][bj][m][n], 0, 0, 0); __builtin_amdgcn_s_setprio(0); } while (0)
; #define PG8_WAIT_V(n) asm volatile("s_waitcnt vmcnt(" #n ")" ::: "memory")
; #define PG8_WAIT_L(n) asm volatile("s_waitcnt lgkmcnt(" #n ")" ::: "memory")
; #define PG8_BAR __builtin_amdgcn_s_barrier()
; #define PG8_SCHED __builtin_amdgcn_sched_barrier(0)
;     __device__ __forceinline__ void operator()(const f32x4 (&acc)[2][2][4][2], const Unit& u, int wr, int wc, int fr, int fq) const {
;         const int row0 = u.pm * BM + wr * 64 + fr;
; #pragma unroll
;         for (int bj = 0; bj < 2; ++bj) {
;             const int col0 = u.pn * BM + bj * HALF + wc * 32 + 8 * fq;
;             if (col0 >= 2880) continue;
;             const float sc = (col0 < 256) ? 0.125f : 1.0f;
; #pragma unroll
;             for (int ai = 0; ai < 2; ++ai)
; #pragma unroll
;                 for (int m = 0; m < 4; ++m) {
;                     f32x4 v0 = acc[ai][bj][m][0] * sc, v1 = acc[ai][bj][m][1] * sc;
; template <class Epi, class Sched, bool ALIGN_EPI = false, bool SP2 = false>
; __device__ __forceinline__ void gemm_phase(PG8_LAS unsigned char* lds, const Gemm g, const Sched& S, const Epi& E) {
;     ...
;             PG8_LDA(At, 1, 1); PG8_STAGE(PG8_SB(1, 0), b3, voffB); PG8_STAGE(PG8_SB(1, 1), b3 + hstep, voffB); PG8_STAGE(PG8_SA(1, 0), a3, voffA);
;             PG8_WAIT_V(8); PG8_WAIT_L(0); PG8_BAR; PG8_MMA(1, 0, At, B0); PG8_MMA(1, 1, At, B1); PG8_BAR; PG8_SCHED;
	s_add_i32 s3, s3, s12
	v_lshl_add_u64 v[216:217], v[216:217], 0, s[28:29]
	s_mov_b32 m0, s3
	ds_read_b128 v[184:187], v154 offset:49152
	ds_read_b128 v[188:191], v154 offset:50176
	ds_read_b128 v[192:195], v154 offset:51200
	ds_read_b128 v[196:199], v154 offset:52224
	ds_read_b128 v[200:203], v154 offset:53248
	ds_read_b128 v[204:207], v154 offset:54272
	ds_read_b128 v[208:211], v154 offset:55296
	ds_read_b128 v[212:215], v154 offset:56320
	global_load_lds_dwordx4 v[216:217], off
	s_add_i32 m0, s3, 0x2000
	s_add_u32 s90, s90, 0x10080
	v_lshl_add_u64 v[216:217], v[218:219], 0, s[28:29]
	s_addc_u32 s91, s91, 0
	s_add_i32 s3, s97, s12
	global_load_lds_dwordx4 v[216:217], off
	v_lshl_add_u64 v[216:217], s[90:91], 0, v[132:133]
	s_mov_b32 m0, s3
	s_nop 0
	global_load_lds_dwordx4 v[216:217], off
	v_lshl_add_u64 v[216:217], s[90:91], 0, v[136:137]
	s_add_i32 m0, s3, 0x2000
	s_nop 0
	global_load_lds_dwordx4 v[216:217], off
	v_lshl_add_u64 v[216:217], v[220:221], 0, s[28:29]
	s_mov_b32 m0, s71
	s_nop 0
	global_load_lds_dwordx4 v[216:217], off
	v_lshl_add_u64 v[216:217], v[222:223], 0, s[28:29]
	s_mov_b32 m0, s72
	s_nop 0
	global_load_lds_dwordx4 v[216:217], off
	s_waitcnt vmcnt(8)
	s_waitcnt lgkmcnt(0)
	s_barrier
	s_setprio 1
	s_waitcnt lgkmcnt(0)
	v_mfma_f32_16x16x32_bf16 v[94:97], v[146:149], v[184:187], v[94:97]
	v_mfma_f32_16x16x32_bf16 v[90:93], v[160:163], v[184:187], v[90:93]
	v_mfma_f32_16x16x32_bf16 v[86:89], v[146:149], v[192:195], v[86:89]
	v_mfma_f32_16x16x32_bf16 v[82:85], v[160:163], v[192:195], v[82:85]
	v_mfma_f32_16x16x32_bf16 v[78:81], v[146:149], v[200:203], v[78:81]
	v_mfma_f32_16x16x32_bf16 v[74:77], v[160:163], v[200:203], v[74:77]
	v_mfma_f32_16x16x32_bf16 v[70:73], v[146:149], v[208:211], v[70:73]
	v_mfma_f32_16x16x32_bf16 v[66:69], v[160:163], v[208:211], v[66:69]
	v_mfma_f32_16x16x32_bf16 v[94:97], v[156:159], v[188:191], v[94:97]
	v_mfma_f32_16x16x32_bf16 v[90:93], v[164:167], v[188:191], v[90:93]
	v_mfma_f32_16x16x32_bf16 v[86:89], v[156:159], v[196:199], v[86:89]
	v_mfma_f32_16x16x32_bf16 v[82:85], v[164:167], v[196:199], v[82:85]
	v_mfma_f32_16x16x32_bf16 v[78:81], v[156:159], v[204:207], v[78:81]
	v_mfma_f32_16x16x32_bf16 v[74:77], v[164:167], v[204:207], v[74:77]
	v_mfma_f32_16x16x32_bf16 v[70:73], v[156:159], v[212:215], v[70:73]
	v_mfma_f32_16x16x32_bf16 v[66:69], v[164:167], v[212:215], v[66:69]
	s_setprio 0
	s_setprio 1
	v_mfma_f32_16x16x32_bf16 v[30:33], v[168:171], v[184:187], v[30:33]
	v_mfma_f32_16x16x32_bf16 v[26:29], v[176:179], v[184:187], v[26:29]
	v_mfma_f32_16x16x32_bf16 v[22:25], v[168:171], v[192:195], v[22:25]
	v_mfma_f32_16x16x32_bf16 v[18:21], v[176:179], v[192:195], v[18:21]
	v_mfma_f32_16x16x32_bf16 v[14:17], v[168:171], v[200:203], v[14:17]
	v_mfma_f32_16x16x32_bf16 v[10:13], v[176:179], v[200:203], v[10:13]
	v_mfma_f32_16x16x32_bf16 v[6:9], v[168:171], v[208:211], v[6:9]
	v_mfma_f32_16x16x32_bf16 v[2:5], v[176:179], v[208:211], v[2:5]
	v_mfma_f32_16x16x32_bf16 v[30:33], v[172:175], v[188:191], v[30:33]
	v_mfma_f32_16x16x32_bf16 v[26:29], v[180:183], v[188:191], v[26:29]
	v_mfma_f32_16x16x32_bf16 v[22:25], v[172:175], v[196:199], v[22:25]
	v_mfma_f32_16x16x32_bf16 v[18:21], v[180:183], v[196:199], v[18:21]
	v_mfma_f32_16x16x32_bf16 v[14:17], v[172:175], v[204:207], v[14:17]
	v_mfma_f32_16x16x32_bf16 v[10:13], v[180:183], v[204:207], v[10:13]
	v_mfma_f32_16x16x32_bf16 v[6:9], v[172:175], v[212:215], v[6:9]
	v_mfma_f32_16x16x32_bf16 v[2:5], v[180:183], v[212:215], v[2:5]
	s_setprio 0
	s_barrier
	s_add_i32 s96, s96, 2
	s_add_u32 s88, s88, 0x100
	s_addc_u32 s89, s89, 0
	s_add_u32 s81, s81, 0x100
	s_addc_u32 s87, s87, 0
	s_cmp_gt_u32 s96, 13
	s_cbranch_scc0 .LBB0_270
	s_and_b64 vcc, exec, s[56:57]
	s_cbranch_vccz .LBB0_273
	s_barrier
.LBB0_273:
	s_cmp_eq_u32 s86, 0
	s_cselect_b32 s0, 0x3e000000, 1.0
	v_mov_b32_e32 v158, s0
	v_mov_b32_e32 v159, s0
	s_and_b32 s0, s86, 0xfffffc
	s_cmp_eq_u32 s0, 4
	s_cselect_b64 s[90:91], -1, 0
	s_mov_b32 s88, 0xff00ff
	s_mov_b32 s89, 0xff00ff
	v_lshl_add_u32 v156, s6, 8, v1
	v_mov_b64_e32 v[160:161], s[18:19]
	v_mad_i64_i32 v[160:161], s[0:1], v156, s95, v[160:161]
	v_and_b32_e32 v162, 0x60, v151
	v_add_u32_e32 v162, v162, v151
	v_lshl_or_b32 v162, s86, 8, v162
	v_lshlrev_b32_e32 v162, 1, v162
	v_mov_b32_e32 v163, 0
	v_lshl_add_u64 v[160:161], v[160:161], 0, v[162:163]
	v_bfe_u32 v164, v1, 3, 1
	v_mul_u32_u24_e32 v162, 0xb3c0, v164
	v_sub_u32_e32 v162, 0, v162
	v_sub_u32_e32 v163, 0, v164
	v_lshl_add_u64 v[160:161], v[160:161], 0, v[162:163]
	s_mov_b32 s0, 0xb400
	s_mov_b32 s1, 0
	v_lshl_add_u64 v[162:163], v[160:161], 0, s[0:1]
	v_pk_mul_f32 v[126:127], v[158:159], v[126:127]
	v_pk_mul_f32 v[128:129], v[158:159], v[128:129]
	v_pk_mul_f32 v[122:123], v[158:159], v[122:123]
	v_pk_mul_f32 v[124:125], v[158:159], v[124:125]
	v_pk_mul_f32 v[62:63], v[158:159], v[62:63]
	v_pk_mul_f32 v[64:65], v[158:159], v[64:65]
	v_pk_mul_f32 v[58:59], v[158:159], v[58:59]
	v_pk_mul_f32 v[60:61], v[158:159], v[60:61]
	s_and_b64 vcc, exec, s[90:91]
	s_cbranch_vccz .Lp2e_ns0
; __device__ __forceinline__ unsigned cvt_pk_bf16(float lo, float hi) { unsigned r; asm volatile("v_cvt_pk_bf16_f32 %0, %1, %2" : "=v"(r) : "v"(lo), "v"(hi)); return r; }
; __device__ __forceinline__ float silu_f(float x) { return x * __builtin_amdgcn_rcpf(1.0f + __expf(-x)); }
;     __device__ __forceinline__ void operator()(const f32x4 (&acc)[2][2][4][2], const Unit& u, int wr, int wc, int fr, int fq) const {
;     ...
;                 for (int m = 0; m < 4; ++m) {
;                     f32x4 v0 = acc[ai][bj][m][0] * sc, v1 = acc[ai][bj][m][1] * sc;
;                     if (col0 >= 1024 && col0 < 2048) {
; #pragma unroll
;                         for (int e = 0; e < 4; ++e) { v0[e] = silu_f(v0[e]); v1[e] = silu_f(v1[e]); } }
;                     u32x4 w; w.x = cvt_pk_bf16(v0[0], v0[1]); w.y = cvt_pk_bf16(v0[2], v0[3]); w.z = cvt_pk_bf16(v1[0], v1[1]); w.w = cvt_pk_bf16(v1[2], v1[3]);
;                     *(u32x4*)(O + (size_t)(row0 + ai * HALF + m * 16) * 2880 + col0) = w;
	v_mul_f32_e32 v166, 0xbfb8aa3b, v126
	v_mul_f32_e32 v167, 0xbfb8aa3b, v127
	v_mul_f32_e32 v168, 0xbfb8aa3b, v128
	v_mul_f32_e32 v169, 0xbfb8aa3b, v129
	v_mul_f32_e32 v170, 0xbfb8aa3b, v122
	v_mul_f32_e32 v171, 0xbfb8aa3b, v123
	v_mul_f32_e32 v172, 0xbfb8aa3b, v124
	v_mul_f32_e32 v173, 0xbfb8aa3b, v125
	v_mul_f32_e32 v174, 0xbfb8aa3b, v62
	v_mul_f32_e32 v175, 0xbfb8aa3b, v63
	v_mul_f32_e32 v176, 0xbfb8aa3b, v64
	v_mul_f32_e32 v177, 0xbfb8aa3b, v65
	v_mul_f32_e32 v178, 0xbfb8aa3b, v58
	v_mul_f32_e32 v179, 0xbfb8aa3b, v59
	v_mul_f32_e32 v180, 0xbfb8aa3b, v60
	v_mul_f32_e32 v181, 0xbfb8aa3b, v61
	v_exp_f32_e32 v166, v166
	v_exp_f32_e32 v167, v167
	v_exp_f32_e32 v168, v168
	v_exp_f32_e32 v169, v169
	v_exp_f32_e32 v170, v170
	v_exp_f32_e32 v171, v171
	v_exp_f32_e32 v172, v172
	v_exp_f32_e32 v173, v173
	v_exp_f32_e32 v174, v174
	v_exp_f32_e32 v175, v175
	v_exp_f32_e32 v176, v176
	v_exp_f32_e32 v177, v177
	v_exp_f32_e32 v178, v178
	v_exp_f32_e32 v179, v179
	v_exp_f32_e32 v180, v180
	v_exp_f32_e32 v181, v181
	v_add_f32_e32 v166, 1.0, v166
	v_add_f32_e32 v167, 1.0, v167
	v_add_f32_e32 v168, 1.0, v168
	v_add_f32_e32 v169, 1.0, v169
	v_add_f32_e32 v170, 1.0, v170
	v_add_f32_e32 v171, 1.0, v171
	v_add_f32_e32 v172, 1.0, v172
	v_add_f32_e32 v173, 1.0, v173
	v_add_f32_e32 v174, 1.0, v174
	v_add_f32_e32 v175, 1.0, v175
	v_add_f32_e32 v176, 1.0, v176
	v_add_f32_e32 v177, 1.0, v177
	v_add_f32_e32 v178, 1.0, v178
	v_add_f32_e32 v179, 1.0, v179
	v_add_f32_e32 v180, 1.0, v180
	v_add_f32_e32 v181, 1.0, v181
	v_rcp_f32_e32 v166, v166
	v_rcp_f32_e32 v167, v167
	v_rcp_f32_e32 v168, v168
	v_rcp_f32_e32 v169, v169
	v_rcp_f32_e32 v170, v170
	v_rcp_f32_e32 v171, v171
	v_rcp_f32_e32 v172, v172
	v_rcp_f32_e32 v173, v173
	v_rcp_f32_e32 v174, v174
	v_rcp_f32_e32 v175, v175
	v_rcp_f32_e32 v176, v176
	v_rcp_f32_e32 v177, v177
	v_rcp_f32_e32 v178, v178
	v_rcp_f32_e32 v179, v179
	v_rcp_f32_e32 v180, v180
	v_rcp_f32_e32 v181, v181
	v_mul_f32_e32 v126, v126, v166
	v_mul_f32_e32 v127, v127, v167
	v_mul_f32_e32 v128, v128, v168
	v_mul_f32_e32 v129, v129, v169
	v_mul_f32_e32 v122, v122, v170
	v_mul_f32_e32 v123, v123, v171
	v_mul_f32_e32 v124, v124, v172
	v_mul_f32_e32 v125, v125, v173
	v_mul_f32_e32 v62, v62, v174
	v_mul_f32_e32 v63, v63, v175
	v_mul_f32_e32 v64, v64, v176
	v_mul_f32_e32 v65, v65, v177
	v_mul_f32_e32 v58, v58, v178
	v_mul_f32_e32 v59, v59, v179
	v_mul_f32_e32 v60, v60, v180
	v_mul_f32_e32 v61, v61, v181
.Lp2e_ns0:
	v_cvt_pk_bf16_f32 v126, v126, v127
	v_cvt_pk_bf16_f32 v127, v128, v129
	v_cvt_pk_bf16_f32 v128, v122, v123
	v_cvt_pk_bf16_f32 v129, v124, v125
	v_cvt_pk_bf16_f32 v62, v62, v63
	v_cvt_pk_bf16_f32 v63, v64, v65
	v_cvt_pk_bf16_f32 v64, v58, v59
	v_cvt_pk_bf16_f32 v65, v60, v61
	s_nop 1
	v_mov_b32_dpp v122, v126 row_ror:8 row_mask:0xf bank_mask:0xf
	v_mov_b32_dpp v123, v127 row_ror:8 row_mask:0xf bank_mask:0xf
	v_mov_b32_dpp v124, v128 row_ror:8 row_mask:0xf bank_mask:0xf
	v_mov_b32_dpp v125, v129 row_ror:8 row_mask:0xf bank_mask:0xf
	v_mov_b32_dpp v58, v62 row_ror:8 row_mask:0xf bank_mask:0xf
	v_mov_b32_dpp v59, v63 row_ror:8 row_mask:0xf bank_mask:0xf
	v_mov_b32_dpp v60, v64 row_ror:8 row_mask:0xf bank_mask:0xf
	v_mov_b32_dpp v61, v65 row_ror:8 row_mask:0xf bank_mask:0xf
	s_nop 0
	v_cndmask_b32_e64 v58, v58, v126, s[88:89]
	v_cndmask_b32_e64 v59, v59, v127, s[88:89]
	v_cndmask_b32_e64 v60, v60, v128, s[88:89]
	v_cndmask_b32_e64 v61, v61, v129, s[88:89]
	v_cndmask_b32_e64 v122, v62, v122, s[88:89]
	v_cndmask_b32_e64 v123, v63, v123, s[88:89]
	v_cndmask_b32_e64 v124, v64, v124, s[88:89]
	v_cndmask_b32_e64 v125, v65, v125, s[88:89]
	global_store_dwordx4 v[160:161], v[58:61], off sc1
	global_store_dwordx4 v[162:163], v[122:125], off sc1
	s_mov_b32 s0, 0x16800
	v_lshl_add_u64 v[160:161], v[160:161], 0, s[0:1]
	v_lshl_add_u64 v[162:163], v[162:163], 0, s[0:1]
	v_pk_mul_f32 v[118:119], v[158:159], v[118:119]
	v_pk_mul_f32 v[120:121], v[158:159], v[120:121]
	v_pk_mul_f32 v[114:115], v[158:159], v[114:115]
	v_pk_mul_f32 v[116:117], v[158:159], v[116:117]
	v_pk_mul_f32 v[54:55], v[158:159], v[54:55]
	v_pk_mul_f32 v[56:57], v[158:159], v[56:57]
	v_pk_mul_f32 v[50:51], v[158:159], v[50:51]
	v_pk_mul_f32 v[52:53], v[158:159], v[52:53]
	s_and_b64 vcc, exec, s[90:91]
	s_cbranch_vccz .Lp2e_ns1
	v_mul_f32_e32 v166, 0xbfb8aa3b, v118
	v_mul_f32_e32 v167, 0xbfb8aa3b, v119
	v_mul_f32_e32 v168, 0xbfb8aa3b, v120
	v_mul_f32_e32 v169, 0xbfb8aa3b, v121
	v_mul_f32_e32 v170, 0xbfb8aa3b, v114
	v_mul_f32_e32 v171, 0xbfb8aa3b, v115
	v_mul_f32_e32 v172, 0xbfb8aa3b, v116
	v_mul_f32_e32 v173, 0xbfb8aa3b, v117
	v_mul_f32_e32 v174, 0xbfb8aa3b, v54
	v_mul_f32_e32 v175, 0xbfb8aa3b, v55
	v_mul_f32_e32 v176, 0xbfb8aa3b, v56
	v_mul_f32_e32 v177, 0xbfb8aa3b, v57
	v_mul_f32_e32 v178, 0xbfb8aa3b, v50
	v_mul_f32_e32 v179, 0xbfb8aa3b, v51
	v_mul_f32_e32 v180, 0xbfb8aa3b, v52
	v_mul_f32_e32 v181, 0xbfb8aa3b, v53
	v_exp_f32_e32 v166, v166
	v_exp_f32_e32 v167, v167
	v_exp_f32_e32 v168, v168
	v_exp_f32_e32 v169, v169
	v_exp_f32_e32 v170, v170
	v_exp_f32_e32 v171, v171
	v_exp_f32_e32 v172, v172
	v_exp_f32_e32 v173, v173
	v_exp_f32_e32 v174, v174
	v_exp_f32_e32 v175, v175
	v_exp_f32_e32 v176, v176
	v_exp_f32_e32 v177, v177
	v_exp_f32_e32 v178, v178
	v_exp_f32_e32 v179, v179
	v_exp_f32_e32 v180, v180
	v_exp_f32_e32 v181, v181
	v_add_f32_e32 v166, 1.0, v166
	v_add_f32_e32 v167, 1.0, v167
	v_add_f32_e32 v168, 1.0, v168
	v_add_f32_e32 v169, 1.0, v169
	v_add_f32_e32 v170, 1.0, v170
	v_add_f32_e32 v171, 1.0, v171
	v_add_f32_e32 v172, 1.0, v172
	v_add_f32_e32 v173, 1.0, v173
	v_add_f32_e32 v174, 1.0, v174
	v_add_f32_e32 v175, 1.0, v175
	v_add_f32_e32 v176, 1.0, v176
	v_add_f32_e32 v177, 1.0, v177
	v_add_f32_e32 v178, 1.0, v178
	v_add_f32_e32 v179, 1.0, v179
	v_add_f32_e32 v180, 1.0, v180
	v_add_f32_e32 v181, 1.0, v181
	v_rcp_f32_e32 v166, v166
	v_rcp_f32_e32 v167, v167
	v_rcp_f32_e32 v168, v168
	v_rcp_f32_e32 v169, v169
	v_rcp_f32_e32 v170, v170
	v_rcp_f32_e32 v171, v171
	v_rcp_f32_e32 v172, v172
	v_rcp_f32_e32 v173, v173
	v_rcp_f32_e32 v174, v174
	v_rcp_f32_e32 v175, v175
	v_rcp_f32_e32 v176, v176
	v_rcp_f32_e32 v177, v177
	v_rcp_f32_e32 v178, v178
	v_rcp_f32_e32 v179, v179
	v_rcp_f32_e32 v180, v180
	v_rcp_f32_e32 v181, v181
	v_mul_f32_e32 v118, v118, v166
	v_mul_f32_e32 v119, v119, v167
	v_mul_f32_e32 v120, v120, v168
	v_mul_f32_e32 v121, v121, v169
	v_mul_f32_e32 v114, v114, v170
	v_mul_f32_e32 v115, v115, v171
	v_mul_f32_e32 v116, v116, v172
	v_mul_f32_e32 v117, v117, v173
	v_mul_f32_e32 v54, v54, v174
	v_mul_f32_e32 v55, v55, v175
	v_mul_f32_e32 v56, v56, v176
	v_mul_f32_e32 v57, v57, v177
	v_mul_f32_e32 v50, v50, v178
	v_mul_f32_e32 v51, v51, v179
	v_mul_f32_e32 v52, v52, v180
	v_mul_f32_e32 v53, v53, v181
; __device__ __forceinline__ unsigned cvt_pk_bf16(float lo, float hi) { unsigned r; asm volatile("v_cvt_pk_bf16_f32 %0, %1, %2" : "=v"(r) : "v"(lo), "v"(hi)); return r; }
; __device__ __forceinline__ float silu_f(float x) { return x * __builtin_amdgcn_rcpf(1.0f + __expf(-x)); }
;     __device__ __forceinline__ void operator()(const f32x4 (&acc)[2][2][4][2], const Unit& u, int wr, int wc, int fr, int fq) const {
;     ...
;                 for (int m = 0; m < 4; ++m) {
;                     f32x4 v0 = acc[ai][bj][m][0] * sc, v1 = acc[ai][bj][m][1] * sc;
;                     if (col0 >= 1024 && col0 < 2048) {
; #pragma unroll
;                         for (int e = 0; e < 4; ++e) { v0[e] = silu_f(v0[e]); v1[e] = silu_f(v1[e]); } }
;                     u32x4 w; w.x = cvt_pk_bf16(v0[0], v0[1]); w.y = cvt_pk_bf16(v0[2], v0[3]); w.z = cvt_pk_bf16(v1[0], v1[1]); w.w = cvt_pk_bf16(v1[2], v1[3]);
;                     *(u32x4*)(O + (size_t)(row0 + ai * HALF + m * 16) * 2880 + col0) = w;
.Lp2e_ns1:
	v_cvt_pk_bf16_f32 v118, v118, v119
	v_cvt_pk_bf16_f32 v119, v120, v121
	v_cvt_pk_bf16_f32 v120, v114, v115
	v_cvt_pk_bf16_f32 v121, v116, v117
	v_cvt_pk_bf16_f32 v54, v54, v55
	v_cvt_pk_bf16_f32 v55, v56, v57
	v_cvt_pk_bf16_f32 v56, v50, v51
	v_cvt_pk_bf16_f32 v57, v52, v53
	s_nop 1
	v_mov_b32_dpp v114, v118 row_ror:8 row_mask:0xf bank_mask:0xf
	v_mov_b32_dpp v115, v119 row_ror:8 row_mask:0xf bank_mask:0xf
	v_mov_b32_dpp v116, v120 row_ror:8 row_mask:0xf bank_mask:0xf
	v_mov_b32_dpp v117, v121 row_ror:8 row_mask:0xf bank_mask:0xf
	v_mov_b32_dpp v50, v54 row_ror:8 row_mask:0xf bank_mask:0xf
	v_mov_b32_dpp v51, v55 row_ror:8 row_mask:0xf bank_mask:0xf
	v_mov_b32_dpp v52, v56 row_ror:8 row_mask:0xf bank_mask:0xf
	v_mov_b32_dpp v53, v57 row_ror:8 row_mask:0xf bank_mask:0xf
	s_nop 0
	v_cndmask_b32_e64 v50, v50, v118, s[88:89]
	v_cndmask_b32_e64 v51, v51, v119, s[88:89]
	v_cndmask_b32_e64 v52, v52, v120, s[88:89]
	v_cndmask_b32_e64 v53, v53, v121, s[88:89]
	v_cndmask_b32_e64 v114, v54, v114, s[88:89]
	v_cndmask_b32_e64 v115, v55, v115, s[88:89]
	v_cndmask_b32_e64 v116, v56, v116, s[88:89]
	v_cndmask_b32_e64 v117, v57, v117, s[88:89]
	global_store_dwordx4 v[160:161], v[50:53], off sc1
	global_store_dwordx4 v[162:163], v[114:117], off sc1
	s_mov_b32 s0, 0x16800
	v_lshl_add_u64 v[160:161], v[160:161], 0, s[0:1]
	v_lshl_add_u64 v[162:163], v[162:163], 0, s[0:1]
	v_pk_mul_f32 v[110:111], v[158:159], v[110:111]
	v_pk_mul_f32 v[112:113], v[158:159], v[112:113]
	v_pk_mul_f32 v[106:107], v[158:159], v[106:107]
	v_pk_mul_f32 v[108:109], v[158:159], v[108:109]
	v_pk_mul_f32 v[46:47], v[158:159], v[46:47]
	v_pk_mul_f32 v[48:49], v[158:159], v[48:49]
	v_pk_mul_f32 v[42:43], v[158:159], v[42:43]
	v_pk_mul_f32 v[44:45], v[158:159], v[44:45]
	s_and_b64 vcc, exec, s[90:91]
	s_cbranch_vccz .Lp2e_ns2
	v_mul_f32_e32 v166, 0xbfb8aa3b, v110
	v_mul_f32_e32 v167, 0xbfb8aa3b, v111
	v_mul_f32_e32 v168, 0xbfb8aa3b, v112
	v_mul_f32_e32 v169, 0xbfb8aa3b, v113
	v_mul_f32_e32 v170, 0xbfb8aa3b, v106
	v_mul_f32_e32 v171, 0xbfb8aa3b, v107
	v_mul_f32_e32 v172, 0xbfb8aa3b, v108
	v_mul_f32_e32 v173, 0xbfb8aa3b, v109
	v_mul_f32_e32 v174, 0xbfb8aa3b, v46
	v_mul_f32_e32 v175, 0xbfb8aa3b, v47
	v_mul_f32_e32 v176, 0xbfb8aa3b, v48
	v_mul_f32_e32 v177, 0xbfb8aa3b, v49
	v_mul_f32_e32 v178, 0xbfb8aa3b, v42
	v_mul_f32_e32 v179, 0xbfb8aa3b, v43
	v_mul_f32_e32 v180, 0xbfb8aa3b, v44
	v_mul_f32_e32 v181, 0xbfb8aa3b, v45
	v_exp_f32_e32 v166, v166
	v_exp_f32_e32 v167, v167
	v_exp_f32_e32 v168, v168
	v_exp_f32_e32 v169, v169
	v_exp_f32_e32 v170, v170
	v_exp_f32_e32 v171, v171
	v_exp_f32_e32 v172, v172
	v_exp_f32_e32 v173, v173
	v_exp_f32_e32 v174, v174
	v_exp_f32_e32 v175, v175
	v_exp_f32_e32 v176, v176
	v_exp_f32_e32 v177, v177
	v_exp_f32_e32 v178, v178
	v_exp_f32_e32 v179, v179
	v_exp_f32_e32 v180, v180
	v_exp_f32_e32 v181, v181
	v_add_f32_e32 v166, 1.0, v166
	v_add_f32_e32 v167, 1.0, v167
	v_add_f32_e32 v168, 1.0, v168
	v_add_f32_e32 v169, 1.0, v169
	v_add_f32_e32 v170, 1.0, v170
	v_add_f32_e32 v171, 1.0, v171
	v_add_f32_e32 v172, 1.0, v172
	v_add_f32_e32 v173, 1.0, v173
	v_add_f32_e32 v174, 1.0, v174
	v_add_f32_e32 v175, 1.0, v175
	v_add_f32_e32 v176, 1.0, v176
	v_add_f32_e32 v177, 1.0, v177
	v_add_f32_e32 v178, 1.0, v178
	v_add_f32_e32 v179, 1.0, v179
	v_add_f32_e32 v180, 1.0, v180
	v_add_f32_e32 v181, 1.0, v181
	v_rcp_f32_e32 v166, v166
	v_rcp_f32_e32 v167, v167
	v_rcp_f32_e32 v168, v168
	v_rcp_f32_e32 v169, v169
	v_rcp_f32_e32 v170, v170
	v_rcp_f32_e32 v171, v171
	v_rcp_f32_e32 v172, v172
	v_rcp_f32_e32 v173, v173
	v_rcp_f32_e32 v174, v174
	v_rcp_f32_e32 v175, v175
	v_rcp_f32_e32 v176, v176
	v_rcp_f32_e32 v177, v177
	v_rcp_f32_e32 v178, v178
	v_rcp_f32_e32 v179, v179
	v_rcp_f32_e32 v180, v180
	v_rcp_f32_e32 v181, v181
	v_mul_f32_e32 v110, v110, v166
	v_mul_f32_e32 v111, v111, v167
	v_mul_f32_e32 v112, v112, v168
	v_mul_f32_e32 v113, v113, v169
	v_mul_f32_e32 v106, v106, v170
	v_mul_f32_e32 v107, v107, v171
	v_mul_f32_e32 v108, v108, v172
	v_mul_f32_e32 v109, v109, v173
	v_mul_f32_e32 v46, v46, v174
	v_mul_f32_e32 v47, v47, v175
	v_mul_f32_e32 v48, v48, v176
	v_mul_f32_e32 v49, v49, v177
	v_mul_f32_e32 v42, v42, v178
	v_mul_f32_e32 v43, v43, v179
	v_mul_f32_e32 v44, v44, v180
	v_mul_f32_e32 v45, v45, v181
; __device__ __forceinline__ unsigned cvt_pk_bf16(float lo, float hi) { unsigned r; asm volatile("v_cvt_pk_bf16_f32 %0, %1, %2" : "=v"(r) : "v"(lo), "v"(hi)); return r; }
; __device__ __forceinline__ float silu_f(float x) { return x * __builtin_amdgcn_rcpf(1.0f + __expf(-x)); }
;     __device__ __forceinline__ void operator()(const f32x4 (&acc)[2][2][4][2], const Unit& u, int wr, int wc, int fr, int fq) const {
;     ...
;                 for (int m = 0; m < 4; ++m) {
;                     f32x4 v0 = acc[ai][bj][m][0] * sc, v1 = acc[ai][bj][m][1] * sc;
;                     if (col0 >= 1024 && col0 < 2048) {
; #pragma unroll
;                         for (int e = 0; e < 4; ++e) { v0[e] = silu_f(v0[e]); v1[e] = silu_f(v1[e]); } }
;                     u32x4 w; w.x = cvt_pk_bf16(v0[0], v0[1]); w.y = cvt_pk_bf16(v0[2], v0[3]); w.z = cvt_pk_bf16(v1[0], v1[1]); w.w = cvt_pk_bf16(v1[2], v1[3]);
;                     *(u32x4*)(O + (size_t)(row0 + ai * HALF + m * 16) * 2880 + col0) = w;
.Lp2e_ns2:
	v_cvt_pk_bf16_f32 v110, v110, v111
	v_cvt_pk_bf16_f32 v111, v112, v113
	v_cvt_pk_bf16_f32 v112, v106, v107
	v_cvt_pk_bf16_f32 v113, v108, v109
	v_cvt_pk_bf16_f32 v46, v46, v47
	v_cvt_pk_bf16_f32 v47, v48, v49
	v_cvt_pk_bf16_f32 v48, v42, v43
	v_cvt_pk_bf16_f32 v49, v44, v45
	s_nop 1
	v_mov_b32_dpp v106, v110 row_ror:8 row_mask:0xf bank_mask:0xf
	v_mov_b32_dpp v107, v111 row_ror:8 row_mask:0xf bank_mask:0xf
	v_mov_b32_dpp v108, v112 row_ror:8 row_mask:0xf bank_mask:0xf
	v_mov_b32_dpp v109, v113 row_ror:8 row_mask:0xf bank_mask:0xf
	v_mov_b32_dpp v42, v46 row_ror:8 row_mask:0xf bank_mask:0xf
	v_mov_b32_dpp v43, v47 row_ror:8 row_mask:0xf bank_mask:0xf
	v_mov_b32_dpp v44, v48 row_ror:8 row_mask:0xf bank_mask:0xf
	v_mov_b32_dpp v45, v49 row_ror:8 row_mask:0xf bank_mask:0xf
	s_nop 0
	v_cndmask_b32_e64 v42, v42, v110, s[88:89]
	v_cndmask_b32_e64 v43, v43, v111, s[88:89]
	v_cndmask_b32_e64 v44, v44, v112, s[88:89]
	v_cndmask_b32_e64 v45, v45, v113, s[88:89]
	v_cndmask_b32_e64 v106, v46, v106, s[88:89]
	v_cndmask_b32_e64 v107, v47, v107, s[88:89]
	v_cndmask_b32_e64 v108, v48, v108, s[88:89]
	v_cndmask_b32_e64 v109, v49, v109, s[88:89]
	global_store_dwordx4 v[160:161], v[42:45], off sc1
	global_store_dwordx4 v[162:163], v[106:109], off sc1
	s_mov_b32 s0, 0x16800
	v_lshl_add_u64 v[160:161], v[160:161], 0, s[0:1]
	v_lshl_add_u64 v[162:163], v[162:163], 0, s[0:1]
	v_pk_mul_f32 v[102:103], v[158:159], v[102:103]
	v_pk_mul_f32 v[104:105], v[158:159], v[104:105]
	v_pk_mul_f32 v[98:99], v[158:159], v[98:99]
	v_pk_mul_f32 v[100:101], v[158:159], v[100:101]
	v_pk_mul_f32 v[38:39], v[158:159], v[38:39]
	v_pk_mul_f32 v[40:41], v[158:159], v[40:41]
	v_pk_mul_f32 v[34:35], v[158:159], v[34:35]
	v_pk_mul_f32 v[36:37], v[158:159], v[36:37]
	s_and_b64 vcc, exec, s[90:91]
	s_cbranch_vccz .Lp2e_ns3
	v_mul_f32_e32 v166, 0xbfb8aa3b, v102
	v_mul_f32_e32 v167, 0xbfb8aa3b, v103
	v_mul_f32_e32 v168, 0xbfb8aa3b, v104
	v_mul_f32_e32 v169, 0xbfb8aa3b, v105
	v_mul_f32_e32 v170, 0xbfb8aa3b, v98
	v_mul_f32_e32 v171, 0xbfb8aa3b, v99
	v_mul_f32_e32 v172, 0xbfb8aa3b, v100
	v_mul_f32_e32 v173, 0xbfb8aa3b, v101
	v_mul_f32_e32 v174, 0xbfb8aa3b, v38
	v_mul_f32_e32 v175, 0xbfb8aa3b, v39
	v_mul_f32_e32 v176, 0xbfb8aa3b, v40
	v_mul_f32_e32 v177, 0xbfb8aa3b, v41
	v_mul_f32_e32 v178, 0xbfb8aa3b, v34
	v_mul_f32_e32 v179, 0xbfb8aa3b, v35
	v_mul_f32_e32 v180, 0xbfb8aa3b, v36
	v_mul_f32_e32 v181, 0xbfb8aa3b, v37
	v_exp_f32_e32 v166, v166
	v_exp_f32_e32 v167, v167
	v_exp_f32_e32 v168, v168
	v_exp_f32_e32 v169, v169
	v_exp_f32_e32 v170, v170
	v_exp_f32_e32 v171, v171
	v_exp_f32_e32 v172, v172
	v_exp_f32_e32 v173, v173
	v_exp_f32_e32 v174, v174
	v_exp_f32_e32 v175, v175
	v_exp_f32_e32 v176, v176
	v_exp_f32_e32 v177, v177
	v_exp_f32_e32 v178, v178
	v_exp_f32_e32 v179, v179
	v_exp_f32_e32 v180, v180
	v_exp_f32_e32 v181, v181
	v_add_f32_e32 v166, 1.0, v166
	v_add_f32_e32 v167, 1.0, v167
	v_add_f32_e32 v168, 1.0, v168
	v_add_f32_e32 v169, 1.0, v169
	v_add_f32_e32 v170, 1.0, v170
	v_add_f32_e32 v171, 1.0, v171
	v_add_f32_e32 v172, 1.0, v172
	v_add_f32_e32 v173, 1.0, v173
	v_add_f32_e32 v174, 1.0, v174
	v_add_f32_e32 v175, 1.0, v175
	v_add_f32_e32 v176, 1.0, v176
	v_add_f32_e32 v177, 1.0, v177
	v_add_f32_e32 v178, 1.0, v178
	v_add_f32_e32 v179, 1.0, v179
	v_add_f32_e32 v180, 1.0, v180
	v_add_f32_e32 v181, 1.0, v181
	v_rcp_f32_e32 v166, v166
	v_rcp_f32_e32 v167, v167
	v_rcp_f32_e32 v168, v168
	v_rcp_f32_e32 v169, v169
	v_rcp_f32_e32 v170, v170
	v_rcp_f32_e32 v171, v171
	v_rcp_f32_e32 v172, v172
	v_rcp_f32_e32 v173, v173
	v_rcp_f32_e32 v174, v174
	v_rcp_f32_e32 v175, v175
	v_rcp_f32_e32 v176, v176
	v_rcp_f32_e32 v177, v177
	v_rcp_f32_e32 v178, v178
	v_rcp_f32_e32 v179, v179
	v_rcp_f32_e32 v180, v180
	v_rcp_f32_e32 v181, v181
	v_mul_f32_e32 v102, v102, v166
	v_mul_f32_e32 v103, v103, v167
	v_mul_f32_e32 v104, v104, v168
	v_mul_f32_e32 v105, v105, v169
	v_mul_f32_e32 v98, v98, v170
	v_mul_f32_e32 v99, v99, v171
	v_mul_f32_e32 v100, v100, v172
	v_mul_f32_e32 v101, v101, v173
	v_mul_f32_e32 v38, v38, v174
	v_mul_f32_e32 v39, v39, v175
	v_mul_f32_e32 v40, v40, v176
	v_mul_f32_e32 v41, v41, v177
	v_mul_f32_e32 v34, v34, v178
	v_mul_f32_e32 v35, v35, v179
	v_mul_f32_e32 v36, v36, v180
	v_mul_f32_e32 v37, v37, v181
; __device__ __forceinline__ unsigned cvt_pk_bf16(float lo, float hi) { unsigned r; asm volatile("v_cvt_pk_bf16_f32 %0, %1, %2" : "=v"(r) : "v"(lo), "v"(hi)); return r; }
; __device__ __forceinline__ float silu_f(float x) { return x * __builtin_amdgcn_rcpf(1.0f + __expf(-x)); }
;     __device__ __forceinline__ void operator()(const f32x4 (&acc)[2][2][4][2], const Unit& u, int wr, int wc, int fr, int fq) const {
;     ...
;             for (int ai = 0; ai < 2; ++ai)
; #pragma unroll
;                 for (int m = 0; m < 4; ++m) {
;                     f32x4 v0 = acc[ai][bj][m][0] * sc, v1 = acc[ai][bj][m][1] * sc;
;                     if (col0 >= 1024 && col0 < 2048) {
; #pragma unroll
;                         for (int e = 0; e < 4; ++e) { v0[e] = silu_f(v0[e]); v1[e] = silu_f(v1[e]); } }
;                     u32x4 w; w.x = cvt_pk_bf16(v0[0], v0[1]); w.y = cvt_pk_bf16(v0[2], v0[3]); w.z = cvt_pk_bf16(v1[0], v1[1]); w.w = cvt_pk_bf16(v1[2], v1[3]);
;                     *(u32x4*)(O + (size_t)(row0 + ai * HALF + m * 16) * 2880 + col0) = w;
.Lp2e_ns3:
	v_cvt_pk_bf16_f32 v102, v102, v103
	v_cvt_pk_bf16_f32 v103, v104, v105
	v_cvt_pk_bf16_f32 v104, v98, v99
	v_cvt_pk_bf16_f32 v105, v100, v101
	v_cvt_pk_bf16_f32 v38, v38, v39
	v_cvt_pk_bf16_f32 v39, v40, v41
	v_cvt_pk_bf16_f32 v40, v34, v35
	v_cvt_pk_bf16_f32 v41, v36, v37
	s_nop 1
	v_mov_b32_dpp v98, v102 row_ror:8 row_mask:0xf bank_mask:0xf
	v_mov_b32_dpp v99, v103 row_ror:8 row_mask:0xf bank_mask:0xf
	v_mov_b32_dpp v100, v104 row_ror:8 row_mask:0xf bank_mask:0xf
	v_mov_b32_dpp v101, v105 row_ror:8 row_mask:0xf bank_mask:0xf
	v_mov_b32_dpp v34, v38 row_ror:8 row_mask:0xf bank_mask:0xf
	v_mov_b32_dpp v35, v39 row_ror:8 row_mask:0xf bank_mask:0xf
	v_mov_b32_dpp v36, v40 row_ror:8 row_mask:0xf bank_mask:0xf
	v_mov_b32_dpp v37, v41 row_ror:8 row_mask:0xf bank_mask:0xf
	s_nop 0
	v_cndmask_b32_e64 v34, v34, v102, s[88:89]
	v_cndmask_b32_e64 v35, v35, v103, s[88:89]
	v_cndmask_b32_e64 v36, v36, v104, s[88:89]
	v_cndmask_b32_e64 v37, v37, v105, s[88:89]
	v_cndmask_b32_e64 v98, v38, v98, s[88:89]
	v_cndmask_b32_e64 v99, v39, v99, s[88:89]
	v_cndmask_b32_e64 v100, v40, v100, s[88:89]
	v_cndmask_b32_e64 v101, v41, v101, s[88:89]
	global_store_dwordx4 v[160:161], v[34:37], off sc1
	global_store_dwordx4 v[162:163], v[98:101], off sc1
	s_mov_b32 s0, 0x70800
	v_lshl_add_u64 v[160:161], v[160:161], 0, s[0:1]
	v_lshl_add_u64 v[162:163], v[162:163], 0, s[0:1]
	v_pk_mul_f32 v[94:95], v[158:159], v[94:95]
	v_pk_mul_f32 v[96:97], v[158:159], v[96:97]
	v_pk_mul_f32 v[90:91], v[158:159], v[90:91]
	v_pk_mul_f32 v[92:93], v[158:159], v[92:93]
	v_pk_mul_f32 v[30:31], v[158:159], v[30:31]
	v_pk_mul_f32 v[32:33], v[158:159], v[32:33]
	v_pk_mul_f32 v[26:27], v[158:159], v[26:27]
	v_pk_mul_f32 v[28:29], v[158:159], v[28:29]
	s_and_b64 vcc, exec, s[90:91]
	s_cbranch_vccz .Lp2e_ns4
	v_mul_f32_e32 v166, 0xbfb8aa3b, v94
	v_mul_f32_e32 v167, 0xbfb8aa3b, v95
	v_mul_f32_e32 v168, 0xbfb8aa3b, v96
	v_mul_f32_e32 v169, 0xbfb8aa3b, v97
	v_mul_f32_e32 v170, 0xbfb8aa3b, v90
	v_mul_f32_e32 v171, 0xbfb8aa3b, v91
	v_mul_f32_e32 v172, 0xbfb8aa3b, v92
	v_mul_f32_e32 v173, 0xbfb8aa3b, v93
	v_mul_f32_e32 v174, 0xbfb8aa3b, v30
	v_mul_f32_e32 v175, 0xbfb8aa3b, v31
	v_mul_f32_e32 v176, 0xbfb8aa3b, v32
	v_mul_f32_e32 v177, 0xbfb8aa3b, v33
	v_mul_f32_e32 v178, 0xbfb8aa3b, v26
	v_mul_f32_e32 v179, 0xbfb8aa3b, v27
	v_mul_f32_e32 v180, 0xbfb8aa3b, v28
	v_mul_f32_e32 v181, 0xbfb8aa3b, v29
	v_exp_f32_e32 v166, v166
	v_exp_f32_e32 v167, v167
	v_exp_f32_e32 v168, v168
	v_exp_f32_e32 v169, v169
	v_exp_f32_e32 v170, v170
	v_exp_f32_e32 v171, v171
	v_exp_f32_e32 v172, v172
	v_exp_f32_e32 v173, v173
	v_exp_f32_e32 v174, v174
	v_exp_f32_e32 v175, v175
	v_exp_f32_e32 v176, v176
	v_exp_f32_e32 v177, v177
	v_exp_f32_e32 v178, v178
	v_exp_f32_e32 v179, v179
	v_exp_f32_e32 v180, v180
	v_exp_f32_e32 v181, v181
	v_add_f32_e32 v166, 1.0, v166
	v_add_f32_e32 v167, 1.0, v167
	v_add_f32_e32 v168, 1.0, v168
	v_add_f32_e32 v169, 1.0, v169
	v_add_f32_e32 v170, 1.0, v170
	v_add_f32_e32 v171, 1.0, v171
	v_add_f32_e32 v172, 1.0, v172
	v_add_f32_e32 v173, 1.0, v173
	v_add_f32_e32 v174, 1.0, v174
	v_add_f32_e32 v175, 1.0, v175
	v_add_f32_e32 v176, 1.0, v176
	v_add_f32_e32 v177, 1.0, v177
	v_add_f32_e32 v178, 1.0, v178
	v_add_f32_e32 v179, 1.0, v179
	v_add_f32_e32 v180, 1.0, v180
	v_add_f32_e32 v181, 1.0, v181
	v_rcp_f32_e32 v166, v166
	v_rcp_f32_e32 v167, v167
	v_rcp_f32_e32 v168, v168
	v_rcp_f32_e32 v169, v169
	v_rcp_f32_e32 v170, v170
	v_rcp_f32_e32 v171, v171
	v_rcp_f32_e32 v172, v172
	v_rcp_f32_e32 v173, v173
	v_rcp_f32_e32 v174, v174
	v_rcp_f32_e32 v175, v175
	v_rcp_f32_e32 v176, v176
	v_rcp_f32_e32 v177, v177
	v_rcp_f32_e32 v178, v178
	v_rcp_f32_e32 v179, v179
	v_rcp_f32_e32 v180, v180
	v_rcp_f32_e32 v181, v181
	v_mul_f32_e32 v94, v94, v166
	v_mul_f32_e32 v95, v95, v167
	v_mul_f32_e32 v96, v96, v168
	v_mul_f32_e32 v97, v97, v169
	v_mul_f32_e32 v90, v90, v170
	v_mul_f32_e32 v91, v91, v171
	v_mul_f32_e32 v92, v92, v172
	v_mul_f32_e32 v93, v93, v173
	v_mul_f32_e32 v30, v30, v174
	v_mul_f32_e32 v31, v31, v175
	v_mul_f32_e32 v32, v32, v176
	v_mul_f32_e32 v33, v33, v177
	v_mul_f32_e32 v26, v26, v178
	v_mul_f32_e32 v27, v27, v179
	v_mul_f32_e32 v28, v28, v180
	v_mul_f32_e32 v29, v29, v181
.Lp2e_ns4:
	v_cvt_pk_bf16_f32 v94, v94, v95
	v_cvt_pk_bf16_f32 v95, v96, v97
	v_cvt_pk_bf16_f32 v96, v90, v91
	v_cvt_pk_bf16_f32 v97, v92, v93
	v_cvt_pk_bf16_f32 v30, v30, v31
	v_cvt_pk_bf16_f32 v31, v32, v33
	v_cvt_pk_bf16_f32 v32, v26, v27
	v_cvt_pk_bf16_f32 v33, v28, v29
	s_nop 1
	v_mov_b32_dpp v90, v94 row_ror:8 row_mask:0xf bank_mask:0xf
	v_mov_b32_dpp v91, v95 row_ror:8 row_mask:0xf bank_mask:0xf
	v_mov_b32_dpp v92, v96 row_ror:8 row_mask:0xf bank_mask:0xf
	v_mov_b32_dpp v93, v97 row_ror:8 row_mask:0xf bank_mask:0xf
	v_mov_b32_dpp v26, v30 row_ror:8 row_mask:0xf bank_mask:0xf
	v_mov_b32_dpp v27, v31 row_ror:8 row_mask:0xf bank_mask:0xf
	v_mov_b32_dpp v28, v32 row_ror:8 row_mask:0xf bank_mask:0xf
	v_mov_b32_dpp v29, v33 row_ror:8 row_mask:0xf bank_mask:0xf
	s_nop 0
	v_cndmask_b32_e64 v26, v26, v94, s[88:89]
	v_cndmask_b32_e64 v27, v27, v95, s[88:89]
	v_cndmask_b32_e64 v28, v28, v96, s[88:89]
	v_cndmask_b32_e64 v29, v29, v97, s[88:89]
	v_cndmask_b32_e64 v90, v30, v90, s[88:89]
	v_cndmask_b32_e64 v91, v31, v91, s[88:89]
	v_cndmask_b32_e64 v92, v32, v92, s[88:89]
	v_cndmask_b32_e64 v93, v33, v93, s[88:89]
	global_store_dwordx4 v[160:161], v[26:29], off sc1
	global_store_dwordx4 v[162:163], v[90:93], off sc1
	s_mov_b32 s0, 0x16800
	v_lshl_add_u64 v[160:161], v[160:161], 0, s[0:1]
	v_lshl_add_u64 v[162:163], v[162:163], 0, s[0:1]
	v_pk_mul_f32 v[86:87], v[158:159], v[86:87]
	v_pk_mul_f32 v[88:89], v[158:159], v[88:89]
	v_pk_mul_f32 v[82:83], v[158:159], v[82:83]
	v_pk_mul_f32 v[84:85], v[158:159], v[84:85]
	v_pk_mul_f32 v[22:23], v[158:159], v[22:23]
	v_pk_mul_f32 v[24:25], v[158:159], v[24:25]
	v_pk_mul_f32 v[18:19], v[158:159], v[18:19]
	v_pk_mul_f32 v[20:21], v[158:159], v[20:21]
	s_and_b64 vcc, exec, s[90:91]
	s_cbranch_vccz .Lp2e_ns5
; __device__ __forceinline__ unsigned cvt_pk_bf16(float lo, float hi) { unsigned r; asm volatile("v_cvt_pk_bf16_f32 %0, %1, %2" : "=v"(r) : "v"(lo), "v"(hi)); return r; }
; __device__ __forceinline__ float silu_f(float x) { return x * __builtin_amdgcn_rcpf(1.0f + __expf(-x)); }
;     __device__ __forceinline__ void operator()(const f32x4 (&acc)[2][2][4][2], const Unit& u, int wr, int wc, int fr, int fq) const {
;     ...
;                 for (int m = 0; m < 4; ++m) {
;                     f32x4 v0 = acc[ai][bj][m][0] * sc, v1 = acc[ai][bj][m][1] * sc;
;                     if (col0 >= 1024 && col0 < 2048) {
; #pragma unroll
;                         for (int e = 0; e < 4; ++e) { v0[e] = silu_f(v0[e]); v1[e] = silu_f(v1[e]); } }
;                     u32x4 w; w.x = cvt_pk_bf16(v0[0], v0[1]); w.y = cvt_pk_bf16(v0[2], v0[3]); w.z = cvt_pk_bf16(v1[0], v1[1]); w.w = cvt_pk_bf16(v1[2], v1[3]);
;                     *(u32x4*)(O + (size_t)(row0 + ai * HALF + m * 16) * 2880 + col0) = w;
	v_mul_f32_e32 v166, 0xbfb8aa3b, v86
	v_mul_f32_e32 v167, 0xbfb8aa3b, v87
	v_mul_f32_e32 v168, 0xbfb8aa3b, v88
	v_mul_f32_e32 v169, 0xbfb8aa3b, v89
	v_mul_f32_e32 v170, 0xbfb8aa3b, v82
	v_mul_f32_e32 v171, 0xbfb8aa3b, v83
	v_mul_f32_e32 v172, 0xbfb8aa3b, v84
	v_mul_f32_e32 v173, 0xbfb8aa3b, v85
	v_mul_f32_e32 v174, 0xbfb8aa3b, v22
	v_mul_f32_e32 v175, 0xbfb8aa3b, v23
	v_mul_f32_e32 v176, 0xbfb8aa3b, v24
	v_mul_f32_e32 v177, 0xbfb8aa3b, v25
	v_mul_f32_e32 v178, 0xbfb8aa3b, v18
	v_mul_f32_e32 v179, 0xbfb8aa3b, v19
	v_mul_f32_e32 v180, 0xbfb8aa3b, v20
	v_mul_f32_e32 v181, 0xbfb8aa3b, v21
	v_exp_f32_e32 v166, v166
	v_exp_f32_e32 v167, v167
	v_exp_f32_e32 v168, v168
	v_exp_f32_e32 v169, v169
	v_exp_f32_e32 v170, v170
	v_exp_f32_e32 v171, v171
	v_exp_f32_e32 v172, v172
	v_exp_f32_e32 v173, v173
	v_exp_f32_e32 v174, v174
	v_exp_f32_e32 v175, v175
	v_exp_f32_e32 v176, v176
	v_exp_f32_e32 v177, v177
	v_exp_f32_e32 v178, v178
	v_exp_f32_e32 v179, v179
	v_exp_f32_e32 v180, v180
	v_exp_f32_e32 v181, v181
	v_add_f32_e32 v166, 1.0, v166
	v_add_f32_e32 v167, 1.0, v167
	v_add_f32_e32 v168, 1.0, v168
	v_add_f32_e32 v169, 1.0, v169
	v_add_f32_e32 v170, 1.0, v170
	v_add_f32_e32 v171, 1.0, v171
	v_add_f32_e32 v172, 1.0, v172
	v_add_f32_e32 v173, 1.0, v173
	v_add_f32_e32 v174, 1.0, v174
	v_add_f32_e32 v175, 1.0, v175
	v_add_f32_e32 v176, 1.0, v176
	v_add_f32_e32 v177, 1.0, v177
	v_add_f32_e32 v178, 1.0, v178
	v_add_f32_e32 v179, 1.0, v179
	v_add_f32_e32 v180, 1.0, v180
	v_add_f32_e32 v181, 1.0, v181
	v_rcp_f32_e32 v166, v166
	v_rcp_f32_e32 v167, v167
	v_rcp_f32_e32 v168, v168
	v_rcp_f32_e32 v169, v169
	v_rcp_f32_e32 v170, v170
	v_rcp_f32_e32 v171, v171
	v_rcp_f32_e32 v172, v172
	v_rcp_f32_e32 v173, v173
	v_rcp_f32_e32 v174, v174
	v_rcp_f32_e32 v175, v175
	v_rcp_f32_e32 v176, v176
	v_rcp_f32_e32 v177, v177
	v_rcp_f32_e32 v178, v178
	v_rcp_f32_e32 v179, v179
	v_rcp_f32_e32 v180, v180
	v_rcp_f32_e32 v181, v181
	v_mul_f32_e32 v86, v86, v166
	v_mul_f32_e32 v87, v87, v167
	v_mul_f32_e32 v88, v88, v168
	v_mul_f32_e32 v89, v89, v169
	v_mul_f32_e32 v82, v82, v170
	v_mul_f32_e32 v83, v83, v171
	v_mul_f32_e32 v84, v84, v172
	v_mul_f32_e32 v85, v85, v173
	v_mul_f32_e32 v22, v22, v174
	v_mul_f32_e32 v23, v23, v175
	v_mul_f32_e32 v24, v24, v176
	v_mul_f32_e32 v25, v25, v177
	v_mul_f32_e32 v18, v18, v178
	v_mul_f32_e32 v19, v19, v179
	v_mul_f32_e32 v20, v20, v180
	v_mul_f32_e32 v21, v21, v181
.Lp2e_ns5:
	v_cvt_pk_bf16_f32 v86, v86, v87
	v_cvt_pk_bf16_f32 v87, v88, v89
	v_cvt_pk_bf16_f32 v88, v82, v83
	v_cvt_pk_bf16_f32 v89, v84, v85
	v_cvt_pk_bf16_f32 v22, v22, v23
	v_cvt_pk_bf16_f32 v23, v24, v25
	v_cvt_pk_bf16_f32 v24, v18, v19
	v_cvt_pk_bf16_f32 v25, v20, v21
	s_nop 1
	v_mov_b32_dpp v82, v86 row_ror:8 row_mask:0xf bank_mask:0xf
	v_mov_b32_dpp v83, v87 row_ror:8 row_mask:0xf bank_mask:0xf
	v_mov_b32_dpp v84, v88 row_ror:8 row_mask:0xf bank_mask:0xf
	v_mov_b32_dpp v85, v89 row_ror:8 row_mask:0xf bank_mask:0xf
	v_mov_b32_dpp v18, v22 row_ror:8 row_mask:0xf bank_mask:0xf
	v_mov_b32_dpp v19, v23 row_ror:8 row_mask:0xf bank_mask:0xf
	v_mov_b32_dpp v20, v24 row_ror:8 row_mask:0xf bank_mask:0xf
	v_mov_b32_dpp v21, v25 row_ror:8 row_mask:0xf bank_mask:0xf
	s_nop 0
	v_cndmask_b32_e64 v18, v18, v86, s[88:89]
	v_cndmask_b32_e64 v19, v19, v87, s[88:89]
	v_cndmask_b32_e64 v20, v20, v88, s[88:89]
	v_cndmask_b32_e64 v21, v21, v89, s[88:89]
	v_cndmask_b32_e64 v82, v22, v82, s[88:89]
	v_cndmask_b32_e64 v83, v23, v83, s[88:89]
	v_cndmask_b32_e64 v84, v24, v84, s[88:89]
	v_cndmask_b32_e64 v85, v25, v85, s[88:89]
	global_store_dwordx4 v[160:161], v[18:21], off sc1
	global_store_dwordx4 v[162:163], v[82:85], off sc1
	s_mov_b32 s0, 0x16800
	v_lshl_add_u64 v[160:161], v[160:161], 0, s[0:1]
	v_lshl_add_u64 v[162:163], v[162:163], 0, s[0:1]
	v_pk_mul_f32 v[78:79], v[158:159], v[78:79]
	v_pk_mul_f32 v[80:81], v[158:159], v[80:81]
	v_pk_mul_f32 v[74:75], v[158:159], v[74:75]
	v_pk_mul_f32 v[76:77], v[158:159], v[76:77]
	v_pk_mul_f32 v[14:15], v[158:159], v[14:15]
	v_pk_mul_f32 v[16:17], v[158:159], v[16:17]
	v_pk_mul_f32 v[10:11], v[158:159], v[10:11]
	v_pk_mul_f32 v[12:13], v[158:159], v[12:13]
	s_and_b64 vcc, exec, s[90:91]
	s_cbranch_vccz .Lp2e_ns6
	v_mul_f32_e32 v166, 0xbfb8aa3b, v78
	v_mul_f32_e32 v167, 0xbfb8aa3b, v79
	v_mul_f32_e32 v168, 0xbfb8aa3b, v80
	v_mul_f32_e32 v169, 0xbfb8aa3b, v81
	v_mul_f32_e32 v170, 0xbfb8aa3b, v74
	v_mul_f32_e32 v171, 0xbfb8aa3b, v75
	v_mul_f32_e32 v172, 0xbfb8aa3b, v76
	v_mul_f32_e32 v173, 0xbfb8aa3b, v77
	v_mul_f32_e32 v174, 0xbfb8aa3b, v14
	v_mul_f32_e32 v175, 0xbfb8aa3b, v15
	v_mul_f32_e32 v176, 0xbfb8aa3b, v16
	v_mul_f32_e32 v177, 0xbfb8aa3b, v17
	v_mul_f32_e32 v178, 0xbfb8aa3b, v10
	v_mul_f32_e32 v179, 0xbfb8aa3b, v11
	v_mul_f32_e32 v180, 0xbfb8aa3b, v12
	v_mul_f32_e32 v181, 0xbfb8aa3b, v13
	v_exp_f32_e32 v166, v166
	v_exp_f32_e32 v167, v167
	v_exp_f32_e32 v168, v168
	v_exp_f32_e32 v169, v169
	v_exp_f32_e32 v170, v170
	v_exp_f32_e32 v171, v171
	v_exp_f32_e32 v172, v172
	v_exp_f32_e32 v173, v173
	v_exp_f32_e32 v174, v174
	v_exp_f32_e32 v175, v175
	v_exp_f32_e32 v176, v176
	v_exp_f32_e32 v177, v177
	v_exp_f32_e32 v178, v178
	v_exp_f32_e32 v179, v179
	v_exp_f32_e32 v180, v180
	v_exp_f32_e32 v181, v181
	v_add_f32_e32 v166, 1.0, v166
	v_add_f32_e32 v167, 1.0, v167
	v_add_f32_e32 v168, 1.0, v168
	v_add_f32_e32 v169, 1.0, v169
	v_add_f32_e32 v170, 1.0, v170
	v_add_f32_e32 v171, 1.0, v171
	v_add_f32_e32 v172, 1.0, v172
	v_add_f32_e32 v173, 1.0, v173
	v_add_f32_e32 v174, 1.0, v174
	v_add_f32_e32 v175, 1.0, v175
	v_add_f32_e32 v176, 1.0, v176
	v_add_f32_e32 v177, 1.0, v177
	v_add_f32_e32 v178, 1.0, v178
	v_add_f32_e32 v179, 1.0, v179
	v_add_f32_e32 v180, 1.0, v180
	v_add_f32_e32 v181, 1.0, v181
	v_rcp_f32_e32 v166, v166
	v_rcp_f32_e32 v167, v167
	v_rcp_f32_e32 v168, v168
	v_rcp_f32_e32 v169, v169
	v_rcp_f32_e32 v170, v170
	v_rcp_f32_e32 v171, v171
	v_rcp_f32_e32 v172, v172
	v_rcp_f32_e32 v173, v173
	v_rcp_f32_e32 v174, v174
	v_rcp_f32_e32 v175, v175
	v_rcp_f32_e32 v176, v176
	v_rcp_f32_e32 v177, v177
	v_rcp_f32_e32 v178, v178
	v_rcp_f32_e32 v179, v179
	v_rcp_f32_e32 v180, v180
	v_rcp_f32_e32 v181, v181
	v_mul_f32_e32 v78, v78, v166
	v_mul_f32_e32 v79, v79, v167
	v_mul_f32_e32 v80, v80, v168
	v_mul_f32_e32 v81, v81, v169
	v_mul_f32_e32 v74, v74, v170
	v_mul_f32_e32 v75, v75, v171
	v_mul_f32_e32 v76, v76, v172
	v_mul_f32_e32 v77, v77, v173
	v_mul_f32_e32 v14, v14, v174
	v_mul_f32_e32 v15, v15, v175
	v_mul_f32_e32 v16, v16, v176
	v_mul_f32_e32 v17, v17, v177
	v_mul_f32_e32 v10, v10, v178
	v_mul_f32_e32 v11, v11, v179
	v_mul_f32_e32 v12, v12, v180
	v_mul_f32_e32 v13, v13, v181
; __device__ __forceinline__ unsigned cvt_pk_bf16(float lo, float hi) { unsigned r; asm volatile("v_cvt_pk_bf16_f32 %0, %1, %2" : "=v"(r) : "v"(lo), "v"(hi)); return r; }
; __device__ __forceinline__ float silu_f(float x) { return x * __builtin_amdgcn_rcpf(1.0f + __expf(-x)); }
;     __device__ __forceinline__ void operator()(const f32x4 (&acc)[2][2][4][2], const Unit& u, int wr, int wc, int fr, int fq) const {
;     ...
;             for (int ai = 0; ai < 2; ++ai)
; #pragma unroll
;                 for (int m = 0; m < 4; ++m) {
;                     f32x4 v0 = acc[ai][bj][m][0] * sc, v1 = acc[ai][bj][m][1] * sc;
;                     if (col0 >= 1024 && col0 < 2048) {
; #pragma unroll
;                         for (int e = 0; e < 4; ++e) { v0[e] = silu_f(v0[e]); v1[e] = silu_f(v1[e]); } }
;                     u32x4 w; w.x = cvt_pk_bf16(v0[0], v0[1]); w.y = cvt_pk_bf16(v0[2], v0[3]); w.z = cvt_pk_bf16(v1[0], v1[1]); w.w = cvt_pk_bf16(v1[2], v1[3]);
;                     *(u32x4*)(O + (size_t)(row0 + ai * HALF + m * 16) * 2880 + col0) = w;
;                 }
.Lp2e_ns6:
	v_cvt_pk_bf16_f32 v78, v78, v79
	v_cvt_pk_bf16_f32 v79, v80, v81
	v_cvt_pk_bf16_f32 v80, v74, v75
	v_cvt_pk_bf16_f32 v81, v76, v77
	v_cvt_pk_bf16_f32 v14, v14, v15
	v_cvt_pk_bf16_f32 v15, v16, v17
	v_cvt_pk_bf16_f32 v16, v10, v11
	v_cvt_pk_bf16_f32 v17, v12, v13
	s_nop 1
	v_mov_b32_dpp v74, v78 row_ror:8 row_mask:0xf bank_mask:0xf
	v_mov_b32_dpp v75, v79 row_ror:8 row_mask:0xf bank_mask:0xf
	v_mov_b32_dpp v76, v80 row_ror:8 row_mask:0xf bank_mask:0xf
	v_mov_b32_dpp v77, v81 row_ror:8 row_mask:0xf bank_mask:0xf
	v_mov_b32_dpp v10, v14 row_ror:8 row_mask:0xf bank_mask:0xf
	v_mov_b32_dpp v11, v15 row_ror:8 row_mask:0xf bank_mask:0xf
	v_mov_b32_dpp v12, v16 row_ror:8 row_mask:0xf bank_mask:0xf
	v_mov_b32_dpp v13, v17 row_ror:8 row_mask:0xf bank_mask:0xf
	s_nop 0
	v_cndmask_b32_e64 v10, v10, v78, s[88:89]
	v_cndmask_b32_e64 v11, v11, v79, s[88:89]
	v_cndmask_b32_e64 v12, v12, v80, s[88:89]
	v_cndmask_b32_e64 v13, v13, v81, s[88:89]
	v_cndmask_b32_e64 v74, v14, v74, s[88:89]
	v_cndmask_b32_e64 v75, v15, v75, s[88:89]
	v_cndmask_b32_e64 v76, v16, v76, s[88:89]
	v_cndmask_b32_e64 v77, v17, v77, s[88:89]
	global_store_dwordx4 v[160:161], v[10:13], off sc1
	global_store_dwordx4 v[162:163], v[74:77], off sc1
	s_mov_b32 s0, 0x16800
	v_lshl_add_u64 v[160:161], v[160:161], 0, s[0:1]
	v_lshl_add_u64 v[162:163], v[162:163], 0, s[0:1]
	v_pk_mul_f32 v[70:71], v[158:159], v[70:71]
	v_pk_mul_f32 v[72:73], v[158:159], v[72:73]
	v_pk_mul_f32 v[66:67], v[158:159], v[66:67]
	v_pk_mul_f32 v[68:69], v[158:159], v[68:69]
	v_pk_mul_f32 v[6:7], v[158:159], v[6:7]
	v_pk_mul_f32 v[8:9], v[158:159], v[8:9]
	v_pk_mul_f32 v[2:3], v[158:159], v[2:3]
	v_pk_mul_f32 v[4:5], v[158:159], v[4:5]
	s_and_b64 vcc, exec, s[90:91]
	s_cbranch_vccz .Lp2e_ns7
	v_mul_f32_e32 v166, 0xbfb8aa3b, v70
	v_mul_f32_e32 v167, 0xbfb8aa3b, v71
	v_mul_f32_e32 v168, 0xbfb8aa3b, v72
	v_mul_f32_e32 v169, 0xbfb8aa3b, v73
	v_mul_f32_e32 v170, 0xbfb8aa3b, v66
	v_mul_f32_e32 v171, 0xbfb8aa3b, v67
	v_mul_f32_e32 v172, 0xbfb8aa3b, v68
	v_mul_f32_e32 v173, 0xbfb8aa3b, v69
	v_mul_f32_e32 v174, 0xbfb8aa3b, v6
	v_mul_f32_e32 v175, 0xbfb8aa3b, v7
	v_mul_f32_e32 v176, 0xbfb8aa3b, v8
	v_mul_f32_e32 v177, 0xbfb8aa3b, v9
	v_mul_f32_e32 v178, 0xbfb8aa3b, v2
	v_mul_f32_e32 v179, 0xbfb8aa3b, v3
	v_mul_f32_e32 v180, 0xbfb8aa3b, v4
	v_mul_f32_e32 v181, 0xbfb8aa3b, v5
	v_exp_f32_e32 v166, v166
	v_exp_f32_e32 v167, v167
	v_exp_f32_e32 v168, v168
	v_exp_f32_e32 v169, v169
	v_exp_f32_e32 v170, v170
	v_exp_f32_e32 v171, v171
	v_exp_f32_e32 v172, v172
	v_exp_f32_e32 v173, v173
	v_exp_f32_e32 v174, v174
	v_exp_f32_e32 v175, v175
	v_exp_f32_e32 v176, v176
	v_exp_f32_e32 v177, v177
	v_exp_f32_e32 v178, v178
	v_exp_f32_e32 v179, v179
	v_exp_f32_e32 v180, v180
	v_exp_f32_e32 v181, v181
	v_add_f32_e32 v166, 1.0, v166
	v_add_f32_e32 v167, 1.0, v167
	v_add_f32_e32 v168, 1.0, v168
	v_add_f32_e32 v169, 1.0, v169
	v_add_f32_e32 v170, 1.0, v170
	v_add_f32_e32 v171, 1.0, v171
	v_add_f32_e32 v172, 1.0, v172
	v_add_f32_e32 v173, 1.0, v173
	v_add_f32_e32 v174, 1.0, v174
	v_add_f32_e32 v175, 1.0, v175
	v_add_f32_e32 v176, 1.0, v176
	v_add_f32_e32 v177, 1.0, v177
	v_add_f32_e32 v178, 1.0, v178
	v_add_f32_e32 v179, 1.0, v179
	v_add_f32_e32 v180, 1.0, v180
	v_add_f32_e32 v181, 1.0, v181
	v_rcp_f32_e32 v166, v166
	v_rcp_f32_e32 v167, v167
	v_rcp_f32_e32 v168, v168
	v_rcp_f32_e32 v169, v169
	v_rcp_f32_e32 v170, v170
	v_rcp_f32_e32 v171, v171
	v_rcp_f32_e32 v172, v172
	v_rcp_f32_e32 v173, v173
	v_rcp_f32_e32 v174, v174
	v_rcp_f32_e32 v175, v175
	v_rcp_f32_e32 v176, v176
	v_rcp_f32_e32 v177, v177
	v_rcp_f32_e32 v178, v178
	v_rcp_f32_e32 v179, v179
	v_rcp_f32_e32 v180, v180
	v_rcp_f32_e32 v181, v181
	v_mul_f32_e32 v70, v70, v166
	v_mul_f32_e32 v71, v71, v167
	v_mul_f32_e32 v72, v72, v168
	v_mul_f32_e32 v73, v73, v169
	v_mul_f32_e32 v66, v66, v170
	v_mul_f32_e32 v67, v67, v171
	v_mul_f32_e32 v68, v68, v172
	v_mul_f32_e32 v69, v69, v173
	v_mul_f32_e32 v6, v6, v174
	v_mul_f32_e32 v7, v7, v175
	v_mul_f32_e32 v8, v8, v176
	v_mul_f32_e32 v9, v9, v177
	v_mul_f32_e32 v2, v2, v178
	v_mul_f32_e32 v3, v3, v179
	v_mul_f32_e32 v4, v4, v180
	v_mul_f32_e32 v5, v5, v181
.Lp2e_ns7:
	v_cvt_pk_bf16_f32 v70, v70, v71
	v_cvt_pk_bf16_f32 v71, v72, v73
	v_cvt_pk_bf16_f32 v72, v66, v67
	v_cvt_pk_bf16_f32 v73, v68, v69
	v_cvt_pk_bf16_f32 v6, v6, v7
	v_cvt_pk_bf16_f32 v7, v8, v9
	v_cvt_pk_bf16_f32 v8, v2, v3
	v_cvt_pk_bf16_f32 v9, v4, v5
	s_nop 1
	v_mov_b32_dpp v66, v70 row_ror:8 row_mask:0xf bank_mask:0xf
	v_mov_b32_dpp v67, v71 row_ror:8 row_mask:0xf bank_mask:0xf
	v_mov_b32_dpp v68, v72 row_ror:8 row_mask:0xf bank_mask:0xf
	v_mov_b32_dpp v69, v73 row_ror:8 row_mask:0xf bank_mask:0xf
	v_mov_b32_dpp v2, v6 row_ror:8 row_mask:0xf bank_mask:0xf
	v_mov_b32_dpp v3, v7 row_ror:8 row_mask:0xf bank_mask:0xf
	v_mov_b32_dpp v4, v8 row_ror:8 row_mask:0xf bank_mask:0xf
	v_mov_b32_dpp v5, v9 row_ror:8 row_mask:0xf bank_mask:0xf
	s_nop 0
	v_cndmask_b32_e64 v2, v2, v70, s[88:89]
	v_cndmask_b32_e64 v3, v3, v71, s[88:89]
	v_cndmask_b32_e64 v4, v4, v72, s[88:89]
	v_cndmask_b32_e64 v5, v5, v73, s[88:89]
	v_cndmask_b32_e64 v66, v6, v66, s[88:89]
	v_cndmask_b32_e64 v67, v7, v67, s[88:89]
	v_cndmask_b32_e64 v68, v8, v68, s[88:89]
	v_cndmask_b32_e64 v69, v9, v69, s[88:89]
	global_store_dwordx4 v[160:161], v[2:5], off sc1
	global_store_dwordx4 v[162:163], v[66:69], off sc1
	s_andn2_b64 vcc, exec, s[4:5]
	s_mov_b64 s[0:1], -1
	s_cbranch_vccnz .LBB0_262
	s_andn2_b64 vcc, exec, s[26:27]
	s_cbranch_vccnz .LBB0_261
	s_barrier
	s_branch .LBB0_261
